# PG epilogue: sigmoid gates computed per row inside the row loop (overlaps the h2/pp load stream) instead of for the whole tile up front
# baseline (speedup 1.0000x reference)
; #define NTL(p) __builtin_nontemporal_load((const f32x4*)(p))
;     __device__ __forceinline__ void operator()(AccT& acc, const Unit& u, int wr, int wc, int fr, int fq) const {
;     ...
;         const int row0 = u.pm * 256 + wr * 64 + fr, col0 = u.pn * 256 + wc * 32 + 8 * fq;
;         f32x4 hv[2][4]; u32x4 pv[2][2]; float rs[2];
;         const bf16_t* ppbase = (u.L < 256 ? T0 : T1) + (size_t)(u.L & 255) * 65536 + (wr * 64 + fr) * 256 + wc * 32 + 8 * fq;
;         { const float* hr = H + (size_t)row0 * DM + col0; const bf16_t* pp = ppbase;
;           hv[0][0] = NTL(hr); hv[0][1] = NTL(hr + 4); hv[0][2] = NTL(hr + 128); hv[0][3] = NTL(hr + 132);
;           pv[0][0] = *(const u32x4*)pp; pv[0][1] = *(const u32x4*)(pp + 128); rs[0] = rss2[row0]; }
; #pragma unroll
;         for (int r = 0; r < 8; ++r) { const int ai = r >> 2, m = r & 3; const int row = row0 + ai * 128 + m * 16;
;             if (r < 7) { const int rn = row0 + ((r + 1) >> 2) * 128 + ((r + 1) & 3) * 16; const float* hn = H + (size_t)rn * DM + col0; const bf16_t* pn = ppbase + (((r + 1) >> 2) * 128 + ((r + 1) & 3) * 16) * 256;
;                 hv[(r + 1) & 1][0] = NTL(hn); hv[(r + 1) & 1][1] = NTL(hn + 4); hv[(r + 1) & 1][2] = NTL(hn + 128); hv[(r + 1) & 1][3] = NTL(hn + 132);
;                 pv[(r + 1) & 1][0] = *(const u32x4*)pn; pv[(r + 1) & 1][1] = *(const u32x4*)(pn + 128); rs[(r + 1) & 1] = rss2[rn]; }
;             float* hp = H + (size_t)row * DM + col0; float ss = 0.f; const float rstd = rsqrtf(rs[r & 1] * (1.0f / DM) + 1e-6f);
.Lpg_t1sel:
	s_add_u32 s2, s2, s4
	s_addc_u32 s3, s3, 0
	s_add_u32 s2, s2, s38
	s_addc_u32 s3, s3, s39
	v_lshlrev_b32_e32 v201, 9, v205
	v_lshl_add_u32 v201, v222, 4, v201
	v_lshlrev_b32_e32 v204, 3, v222
	v_add_u32_e32 v204, s0, v204
	v_lshlrev_b32_e32 v204, 2, v204
	v_lshl_add_u32 v200, v186, 12, v204
	v_lshlrev_b32_e32 v202, 2, v186
	v_readlane_b32 s72, v255, 14
	v_readlane_b32 s73, v255, 15
	v_readlane_b32 s74, v255, 16
	v_readlane_b32 s75, v255, 17
	v_readfirstlane_b32 s60, v186
	s_nop 3
	global_load_dword v164, v202, s[34:35]
	global_load_dword v165, v202, s[34:35] offset:64
	global_load_dword v166, v202, s[34:35] offset:128
	global_load_dword v167, v202, s[34:35] offset:192
	global_load_dword v170, v202, s[34:35] offset:512
	global_load_dword v171, v202, s[34:35] offset:576
	global_load_dword v172, v202, s[34:35] offset:640
	global_load_dword v173, v202, s[34:35] offset:704
	global_load_dwordx4 v[240:243], v204, s[72:73]
	global_load_dwordx4 v[244:247], v204, s[72:73] offset:16
	global_load_dwordx4 v[248:251], v204, s[72:73] offset:512
	global_load_dwordx4 v[232:235], v204, s[72:73] offset:528
	s_add_u32 s62, s22, 0x0
	s_addc_u32 s63, s23, 0
	global_load_dwordx4 v[130:133], v200, s[62:63] nt
	global_load_dwordx4 v[134:137], v200, s[62:63] offset:16 nt
	global_load_dwordx4 v[138:141], v200, s[62:63] offset:512 nt
	global_load_dwordx4 v[142:145], v200, s[62:63] offset:528 nt
	s_add_u32 s64, s2, 0x0
	s_addc_u32 s65, s3, 0
	global_load_dwordx4 v[146:149], v201, s[64:65]
	global_load_dwordx4 v[150:153], v201, s[64:65] offset:256
	s_add_u32 s62, s22, 0x10000
	s_addc_u32 s63, s23, 0
	global_load_dwordx4 v[184:187], v200, s[62:63] nt
	global_load_dwordx4 v[188:191], v200, s[62:63] offset:16 nt
	global_load_dwordx4 v[192:195], v200, s[62:63] offset:512 nt
	global_load_dwordx4 v[196:199], v200, s[62:63] offset:528 nt
	v_mov_b32_e32 v206, 0xbfb8aa3b
	v_mov_b32_e32 v207, 0xbfb8aa3b
	s_add_u32 s64, s2, 0x2000
	s_addc_u32 s65, s3, 0
	global_load_dwordx4 v[154:157], v201, s[64:65]
	global_load_dwordx4 v[158:161], v201, s[64:65] offset:256
	s_waitcnt vmcnt(16)
	v_fmamk_f32 v164, v164, 0x3a800000, v210
	v_fmamk_f32 v165, v165, 0x3a800000, v210
	v_fmamk_f32 v166, v166, 0x3a800000, v210
	v_fmamk_f32 v167, v167, 0x3a800000, v210
	v_fmamk_f32 v170, v170, 0x3a800000, v210
	v_fmamk_f32 v171, v171, 0x3a800000, v210
	v_fmamk_f32 v172, v172, 0x3a800000, v210
	v_fmamk_f32 v173, v173, 0x3a800000, v210
	v_mul_f32_e32 v205, 0x4b800000, v164
	v_mul_f32_e32 v206, 0x4b800000, v165
	v_mul_f32_e32 v207, 0x4b800000, v166
	v_mul_f32_e32 v225, 0x4b800000, v167
	v_mul_f32_e32 v226, 0x4b800000, v170
	v_mul_f32_e32 v227, 0x4b800000, v171
	v_mul_f32_e32 v228, 0x4b800000, v172
	v_mul_f32_e32 v229, 0x4b800000, v173
	v_cmp_gt_f32_e64 s[62:63], s30, v164
	v_cmp_gt_f32_e64 s[64:65], s30, v165
	v_cmp_gt_f32_e64 s[66:67], s30, v166
	v_cmp_gt_f32_e64 s[68:69], s30, v167
	s_nop 1
	v_cndmask_b32_e64 v164, v164, v205, s[62:63]
	v_cndmask_b32_e64 v165, v165, v206, s[64:65]
	v_cndmask_b32_e64 v166, v166, v207, s[66:67]
	v_cndmask_b32_e64 v167, v167, v225, s[68:69]
	v_rsq_f32_e32 v164, v164
	v_rsq_f32_e32 v165, v165
	v_rsq_f32_e32 v166, v166
	v_rsq_f32_e32 v167, v167
	s_nop 0
	v_mul_f32_e32 v205, 0x45800000, v164
	v_mul_f32_e32 v206, 0x45800000, v165
	v_mul_f32_e32 v207, 0x45800000, v166
	v_mul_f32_e32 v225, 0x45800000, v167
	v_cndmask_b32_e64 v164, v164, v205, s[62:63]
	v_cndmask_b32_e64 v165, v165, v206, s[64:65]
	v_cndmask_b32_e64 v166, v166, v207, s[66:67]
	v_cndmask_b32_e64 v167, v167, v225, s[68:69]
	v_cmp_gt_f32_e64 s[62:63], s30, v170
	v_cmp_gt_f32_e64 s[64:65], s30, v171
	v_cmp_gt_f32_e64 s[66:67], s30, v172
	v_cmp_gt_f32_e64 s[68:69], s30, v173
	s_nop 1
	v_cndmask_b32_e64 v170, v170, v226, s[62:63]
	v_cndmask_b32_e64 v171, v171, v227, s[64:65]
	v_cndmask_b32_e64 v172, v172, v228, s[66:67]
	v_cndmask_b32_e64 v173, v173, v229, s[68:69]
	v_rsq_f32_e32 v170, v170
	v_rsq_f32_e32 v171, v171
	v_rsq_f32_e32 v172, v172
	v_rsq_f32_e32 v173, v173
	s_nop 0
	v_mul_f32_e32 v226, 0x45800000, v170
	v_mul_f32_e32 v227, 0x45800000, v171
	v_mul_f32_e32 v228, 0x45800000, v172
	v_mul_f32_e32 v229, 0x45800000, v173
	v_cndmask_b32_e64 v170, v170, v226, s[62:63]
	v_cndmask_b32_e64 v171, v171, v227, s[64:65]
	v_cndmask_b32_e64 v172, v172, v228, s[66:67]
	v_cndmask_b32_e64 v173, v173, v229, s[68:69]
	v_mov_b32_e32 v206, 0xbfb8aa3b
	v_mov_b32_e32 v207, 0xbfb8aa3b
	v_xor_b32_e32 v225, 16, v203
	v_xor_b32_e32 v226, 32, v203
	v_xor_b32_e32 v227, 48, v203
	v_lshlrev_b32_e32 v225, 2, v225
	v_lshlrev_b32_e32 v226, 2, v226
	v_lshlrev_b32_e32 v227, 2, v227
	v_cmp_eq_u32_e64 s[42:43], 0, v222
	s_waitcnt vmcnt(12)
; __device__ __forceinline__ float bf_lo(unsigned w) { return __uint_as_float(w << 16); }
; __device__ __forceinline__ float bf_hi(unsigned w) { return __uint_as_float(w & 0xffff0000u); }
; __device__ __forceinline__ float sigmoidf_(float x) { return 1.0f / (1.0f + __expf(-x)); }
;     __device__ __forceinline__ void operator()(AccT& acc, const Unit& u, int wr, int wc, int fr, int fq) const {
;     ...
;                 const f32x4 b0 = *(const f32x4*)(bias + col0 + bj * 128), b1 = *(const f32x4*)(bias + col0 + bj * 128 + 4);
;                 const f32x4 p0 = (f32x4){bf_lo(pw.x), bf_hi(pw.x), bf_lo(pw.y), bf_hi(pw.y)}, p1 = (f32x4){bf_lo(pw.z), bf_hi(pw.z), bf_lo(pw.w), bf_hi(pw.w)};
;                 f32x4 g0 = acc[ai][bj][m][0] * rstd + b0, g1 = acc[ai][bj][m][1] * rstd + b1;
; #pragma unroll
;                 for (int j = 0; j < 4; ++j) { g0[j] = sigmoidf_(g0[j]); g1[j] = sigmoidf_(g1[j]); }
;                 const f32x4 v0 = hv[r & 1][2 * bj] + p0 * g0, v1 = hv[r & 1][2 * bj + 1] + p1 * g1;
	v_pk_fma_f32 v[122:123], v[122:123], v[164:165], v[240:241] op_sel_hi:[1,0,1]
	v_pk_fma_f32 v[124:125], v[124:125], v[164:165], v[242:243] op_sel_hi:[1,0,1]
	v_pk_fma_f32 v[114:115], v[114:115], v[164:165], v[244:245] op_sel_hi:[1,0,1]
	v_pk_fma_f32 v[116:117], v[116:117], v[164:165], v[246:247] op_sel_hi:[1,0,1]
	v_pk_fma_f32 v[110:111], v[110:111], v[164:165], v[248:249] op_sel_hi:[1,0,1]
	v_pk_fma_f32 v[112:113], v[112:113], v[164:165], v[250:251] op_sel_hi:[1,0,1]
	v_pk_fma_f32 v[106:107], v[106:107], v[164:165], v[232:233] op_sel_hi:[1,0,1]
	v_pk_fma_f32 v[108:109], v[108:109], v[164:165], v[234:235] op_sel_hi:[1,0,1]
	v_pk_fma_f32 v[126:127], v[126:127], v[164:165], v[240:241] op_sel:[0,1,0] op_sel_hi:[1,1,1]
	v_pk_fma_f32 v[128:129], v[128:129], v[164:165], v[242:243] op_sel:[0,1,0] op_sel_hi:[1,1,1]
	v_pk_fma_f32 v[118:119], v[118:119], v[164:165], v[244:245] op_sel:[0,1,0] op_sel_hi:[1,1,1]
	v_pk_fma_f32 v[120:121], v[120:121], v[164:165], v[246:247] op_sel:[0,1,0] op_sel_hi:[1,1,1]
	v_pk_fma_f32 v[102:103], v[102:103], v[164:165], v[248:249] op_sel:[0,1,0] op_sel_hi:[1,1,1]
	v_pk_fma_f32 v[104:105], v[104:105], v[164:165], v[250:251] op_sel:[0,1,0] op_sel_hi:[1,1,1]
	v_pk_fma_f32 v[98:99], v[98:99], v[164:165], v[232:233] op_sel:[0,1,0] op_sel_hi:[1,1,1]
	v_pk_fma_f32 v[100:101], v[100:101], v[164:165], v[234:235] op_sel:[0,1,0] op_sel_hi:[1,1,1]
	v_pk_fma_f32 v[94:95], v[94:95], v[166:167], v[240:241] op_sel_hi:[1,0,1]
	v_pk_fma_f32 v[96:97], v[96:97], v[166:167], v[242:243] op_sel_hi:[1,0,1]
	v_pk_fma_f32 v[90:91], v[90:91], v[166:167], v[244:245] op_sel_hi:[1,0,1]
	v_pk_fma_f32 v[92:93], v[92:93], v[166:167], v[246:247] op_sel_hi:[1,0,1]
	v_pk_fma_f32 v[86:87], v[86:87], v[166:167], v[248:249] op_sel_hi:[1,0,1]
	v_pk_fma_f32 v[88:89], v[88:89], v[166:167], v[250:251] op_sel_hi:[1,0,1]
	v_pk_fma_f32 v[82:83], v[82:83], v[166:167], v[232:233] op_sel_hi:[1,0,1]
	v_pk_fma_f32 v[84:85], v[84:85], v[166:167], v[234:235] op_sel_hi:[1,0,1]
	v_pk_fma_f32 v[78:79], v[78:79], v[166:167], v[240:241] op_sel:[0,1,0] op_sel_hi:[1,1,1]
	v_pk_fma_f32 v[80:81], v[80:81], v[166:167], v[242:243] op_sel:[0,1,0] op_sel_hi:[1,1,1]
	v_pk_fma_f32 v[74:75], v[74:75], v[166:167], v[244:245] op_sel:[0,1,0] op_sel_hi:[1,1,1]
	v_pk_fma_f32 v[76:77], v[76:77], v[166:167], v[246:247] op_sel:[0,1,0] op_sel_hi:[1,1,1]
	v_pk_fma_f32 v[70:71], v[70:71], v[166:167], v[248:249] op_sel:[0,1,0] op_sel_hi:[1,1,1]
	v_pk_fma_f32 v[72:73], v[72:73], v[166:167], v[250:251] op_sel:[0,1,0] op_sel_hi:[1,1,1]
	v_pk_fma_f32 v[66:67], v[66:67], v[166:167], v[232:233] op_sel:[0,1,0] op_sel_hi:[1,1,1]
	v_pk_fma_f32 v[68:69], v[68:69], v[166:167], v[234:235] op_sel:[0,1,0] op_sel_hi:[1,1,1]
	v_pk_fma_f32 v[62:63], v[62:63], v[170:171], v[240:241] op_sel_hi:[1,0,1]
	v_pk_fma_f32 v[64:65], v[64:65], v[170:171], v[242:243] op_sel_hi:[1,0,1]
	v_pk_fma_f32 v[58:59], v[58:59], v[170:171], v[244:245] op_sel_hi:[1,0,1]
	v_pk_fma_f32 v[60:61], v[60:61], v[170:171], v[246:247] op_sel_hi:[1,0,1]
	v_pk_fma_f32 v[54:55], v[54:55], v[170:171], v[248:249] op_sel_hi:[1,0,1]
	v_pk_fma_f32 v[56:57], v[56:57], v[170:171], v[250:251] op_sel_hi:[1,0,1]
	v_pk_fma_f32 v[50:51], v[50:51], v[170:171], v[232:233] op_sel_hi:[1,0,1]
	v_pk_fma_f32 v[52:53], v[52:53], v[170:171], v[234:235] op_sel_hi:[1,0,1]
	v_pk_fma_f32 v[46:47], v[46:47], v[170:171], v[240:241] op_sel:[0,1,0] op_sel_hi:[1,1,1]
	v_pk_fma_f32 v[48:49], v[48:49], v[170:171], v[242:243] op_sel:[0,1,0] op_sel_hi:[1,1,1]
	v_pk_fma_f32 v[42:43], v[42:43], v[170:171], v[244:245] op_sel:[0,1,0] op_sel_hi:[1,1,1]
	v_pk_fma_f32 v[44:45], v[44:45], v[170:171], v[246:247] op_sel:[0,1,0] op_sel_hi:[1,1,1]
	v_pk_fma_f32 v[38:39], v[38:39], v[170:171], v[248:249] op_sel:[0,1,0] op_sel_hi:[1,1,1]
	v_pk_fma_f32 v[40:41], v[40:41], v[170:171], v[250:251] op_sel:[0,1,0] op_sel_hi:[1,1,1]
	v_pk_fma_f32 v[34:35], v[34:35], v[170:171], v[232:233] op_sel:[0,1,0] op_sel_hi:[1,1,1]
	v_pk_fma_f32 v[36:37], v[36:37], v[170:171], v[234:235] op_sel:[0,1,0] op_sel_hi:[1,1,1]
	v_pk_fma_f32 v[30:31], v[30:31], v[172:173], v[240:241] op_sel_hi:[1,0,1]
	v_pk_fma_f32 v[32:33], v[32:33], v[172:173], v[242:243] op_sel_hi:[1,0,1]
	v_pk_fma_f32 v[26:27], v[26:27], v[172:173], v[244:245] op_sel_hi:[1,0,1]
	v_pk_fma_f32 v[28:29], v[28:29], v[172:173], v[246:247] op_sel_hi:[1,0,1]
	v_pk_fma_f32 v[22:23], v[22:23], v[172:173], v[248:249] op_sel_hi:[1,0,1]
	v_pk_fma_f32 v[24:25], v[24:25], v[172:173], v[250:251] op_sel_hi:[1,0,1]
	v_pk_fma_f32 v[18:19], v[18:19], v[172:173], v[232:233] op_sel_hi:[1,0,1]
	v_pk_fma_f32 v[20:21], v[20:21], v[172:173], v[234:235] op_sel_hi:[1,0,1]
	v_pk_fma_f32 v[14:15], v[14:15], v[172:173], v[240:241] op_sel:[0,1,0] op_sel_hi:[1,1,1]
	v_pk_fma_f32 v[16:17], v[16:17], v[172:173], v[242:243] op_sel:[0,1,0] op_sel_hi:[1,1,1]
	v_pk_fma_f32 v[10:11], v[10:11], v[172:173], v[244:245] op_sel:[0,1,0] op_sel_hi:[1,1,1]
	v_pk_fma_f32 v[12:13], v[12:13], v[172:173], v[246:247] op_sel:[0,1,0] op_sel_hi:[1,1,1]
	v_pk_fma_f32 v[6:7], v[6:7], v[172:173], v[248:249] op_sel:[0,1,0] op_sel_hi:[1,1,1]
	v_pk_fma_f32 v[8:9], v[8:9], v[172:173], v[250:251] op_sel:[0,1,0] op_sel_hi:[1,1,1]
	v_pk_fma_f32 v[2:3], v[2:3], v[172:173], v[232:233] op_sel:[0,1,0] op_sel_hi:[1,1,1]
	v_pk_fma_f32 v[4:5], v[4:5], v[172:173], v[234:235] op_sel:[0,1,0] op_sel_hi:[1,1,1]
	v_pk_mul_f32 v[122:123], v[122:123], v[206:207]
	v_pk_mul_f32 v[124:125], v[124:125], v[206:207]
	v_pk_mul_f32 v[114:115], v[114:115], v[206:207]
	v_pk_mul_f32 v[116:117], v[116:117], v[206:207]
	v_exp_f32_e32 v122, v122
	v_exp_f32_e32 v123, v123
	v_exp_f32_e32 v124, v124
	v_exp_f32_e32 v125, v125
	v_exp_f32_e32 v114, v114
; #define NTS(v, p) __builtin_nontemporal_store((v), (f32x4*)(p))
; __device__ __forceinline__ float bf_lo(unsigned w) { return __uint_as_float(w << 16); }
; __device__ __forceinline__ float bf_hi(unsigned w) { return __uint_as_float(w & 0xffff0000u); }
; __device__ __forceinline__ float sigmoidf_(float x) { return 1.0f / (1.0f + __expf(-x)); }
;     __device__ __forceinline__ void operator()(AccT& acc, const Unit& u, int wr, int wc, int fr, int fq) const {
;     ...
;             float* hp = H + (size_t)row * DM + col0; float ss = 0.f; const float rstd = rsqrtf(rs[r & 1] * (1.0f / DM) + 1e-6f);
; #pragma unroll
;             for (int bj = 0; bj < 2; ++bj) { const u32x4 pw = pv[r & 1][bj];
;                 const f32x4 b0 = *(const f32x4*)(bias + col0 + bj * 128), b1 = *(const f32x4*)(bias + col0 + bj * 128 + 4);
;                 const f32x4 p0 = (f32x4){bf_lo(pw.x), bf_hi(pw.x), bf_lo(pw.y), bf_hi(pw.y)}, p1 = (f32x4){bf_lo(pw.z), bf_hi(pw.z), bf_lo(pw.w), bf_hi(pw.w)};
;                 f32x4 g0 = acc[ai][bj][m][0] * rstd + b0, g1 = acc[ai][bj][m][1] * rstd + b1;
; #pragma unroll
;                 for (int j = 0; j < 4; ++j) { g0[j] = sigmoidf_(g0[j]); g1[j] = sigmoidf_(g1[j]); }
;                 const f32x4 v0 = hv[r & 1][2 * bj] + p0 * g0, v1 = hv[r & 1][2 * bj + 1] + p1 * g1;
;                 NTS(v0, hp + bj * 128); NTS(v1, hp + bj * 128 + 4);
; #pragma unroll
;                 for (int j = 0; j < 4; ++j) ss += v0[j] * v0[j] + v1[j] * v1[j]; }
;             ss += __shfl_xor(ss, 16); ss += __shfl_xor(ss, 32);
	v_exp_f32_e32 v115, v115
	v_exp_f32_e32 v116, v116
	v_exp_f32_e32 v117, v117
	v_pk_add_f32 v[122:123], v[122:123], 1.0 op_sel_hi:[1,0]
	v_pk_add_f32 v[124:125], v[124:125], 1.0 op_sel_hi:[1,0]
	v_pk_add_f32 v[114:115], v[114:115], 1.0 op_sel_hi:[1,0]
	v_pk_add_f32 v[116:117], v[116:117], 1.0 op_sel_hi:[1,0]
	v_rcp_f32_e32 v240, v122
	v_rcp_f32_e32 v241, v123
	v_rcp_f32_e32 v242, v124
	v_rcp_f32_e32 v243, v125
	v_rcp_f32_e32 v244, v114
	v_rcp_f32_e32 v245, v115
	v_rcp_f32_e32 v246, v116
	v_rcp_f32_e32 v247, v117
	v_pk_fma_f32 v[122:123], v[122:123], v[240:241], 1.0 op_sel_hi:[1,1,0] neg_lo:[1,0,0] neg_hi:[1,0,0]
	v_pk_fma_f32 v[124:125], v[124:125], v[242:243], 1.0 op_sel_hi:[1,1,0] neg_lo:[1,0,0] neg_hi:[1,0,0]
	v_pk_fma_f32 v[114:115], v[114:115], v[244:245], 1.0 op_sel_hi:[1,1,0] neg_lo:[1,0,0] neg_hi:[1,0,0]
	v_pk_fma_f32 v[116:117], v[116:117], v[246:247], 1.0 op_sel_hi:[1,1,0] neg_lo:[1,0,0] neg_hi:[1,0,0]
	v_pk_fma_f32 v[122:123], v[122:123], v[240:241], v[240:241]
	v_pk_fma_f32 v[124:125], v[124:125], v[242:243], v[242:243]
	v_pk_fma_f32 v[114:115], v[114:115], v[244:245], v[244:245]
	v_pk_fma_f32 v[116:117], v[116:117], v[246:247], v[246:247]
	v_pk_mul_f32 v[110:111], v[110:111], v[206:207]
	v_pk_mul_f32 v[112:113], v[112:113], v[206:207]
	v_pk_mul_f32 v[106:107], v[106:107], v[206:207]
	v_pk_mul_f32 v[108:109], v[108:109], v[206:207]
	v_exp_f32_e32 v110, v110
	v_exp_f32_e32 v111, v111
	v_exp_f32_e32 v112, v112
	v_exp_f32_e32 v113, v113
	v_exp_f32_e32 v106, v106
	v_exp_f32_e32 v107, v107
	v_exp_f32_e32 v108, v108
	v_exp_f32_e32 v109, v109
	v_pk_add_f32 v[110:111], v[110:111], 1.0 op_sel_hi:[1,0]
	v_pk_add_f32 v[112:113], v[112:113], 1.0 op_sel_hi:[1,0]
	v_pk_add_f32 v[106:107], v[106:107], 1.0 op_sel_hi:[1,0]
	v_pk_add_f32 v[108:109], v[108:109], 1.0 op_sel_hi:[1,0]
	v_rcp_f32_e32 v240, v110
	v_rcp_f32_e32 v241, v111
	v_rcp_f32_e32 v242, v112
	v_rcp_f32_e32 v243, v113
	v_rcp_f32_e32 v244, v106
	v_rcp_f32_e32 v245, v107
	v_rcp_f32_e32 v246, v108
	v_rcp_f32_e32 v247, v109
	v_pk_fma_f32 v[110:111], v[110:111], v[240:241], 1.0 op_sel_hi:[1,1,0] neg_lo:[1,0,0] neg_hi:[1,0,0]
	v_pk_fma_f32 v[112:113], v[112:113], v[242:243], 1.0 op_sel_hi:[1,1,0] neg_lo:[1,0,0] neg_hi:[1,0,0]
	v_pk_fma_f32 v[106:107], v[106:107], v[244:245], 1.0 op_sel_hi:[1,1,0] neg_lo:[1,0,0] neg_hi:[1,0,0]
	v_pk_fma_f32 v[108:109], v[108:109], v[246:247], 1.0 op_sel_hi:[1,1,0] neg_lo:[1,0,0] neg_hi:[1,0,0]
	v_pk_fma_f32 v[110:111], v[110:111], v[240:241], v[240:241]
	v_pk_fma_f32 v[112:113], v[112:113], v[242:243], v[242:243]
	v_pk_fma_f32 v[106:107], v[106:107], v[244:245], v[244:245]
	v_pk_fma_f32 v[108:109], v[108:109], v[246:247], v[246:247]
	s_waitcnt vmcnt(6)
	v_lshlrev_b32_e32 v248, 16, v146
	v_and_b32_e32 v249, 0xffff0000, v146
	v_lshlrev_b32_e32 v250, 16, v147
	v_and_b32_e32 v251, 0xffff0000, v147
	v_fma_f32 v122, v248, v122, v130
	v_fma_f32 v123, v249, v123, v131
	v_fma_f32 v124, v250, v124, v132
	v_fma_f32 v125, v251, v125, v133
	v_pk_mul_f32 v[228:229], v[122:123], v[122:123]
	s_nop 0
	v_pk_fma_f32 v[228:229], v[124:125], v[124:125], v[228:229]
	v_lshlrev_b32_e32 v232, 16, v148
	v_and_b32_e32 v233, 0xffff0000, v148
	v_lshlrev_b32_e32 v234, 16, v149
	v_and_b32_e32 v235, 0xffff0000, v149
	v_fma_f32 v114, v232, v114, v134
	v_fma_f32 v115, v233, v115, v135
	v_fma_f32 v116, v234, v116, v136
	v_fma_f32 v117, v235, v117, v137
	v_pk_fma_f32 v[228:229], v[114:115], v[114:115], v[228:229]
	s_nop 0
	v_pk_fma_f32 v[228:229], v[116:117], v[116:117], v[228:229]
	v_lshlrev_b32_e32 v248, 16, v150
	v_and_b32_e32 v249, 0xffff0000, v150
	v_lshlrev_b32_e32 v250, 16, v151
	v_and_b32_e32 v251, 0xffff0000, v151
	v_fma_f32 v110, v248, v110, v138
	v_fma_f32 v111, v249, v111, v139
	v_fma_f32 v112, v250, v112, v140
	v_fma_f32 v113, v251, v113, v141
	v_pk_fma_f32 v[228:229], v[110:111], v[110:111], v[228:229]
	s_nop 0
	v_pk_fma_f32 v[228:229], v[112:113], v[112:113], v[228:229]
	v_lshlrev_b32_e32 v232, 16, v152
	v_and_b32_e32 v233, 0xffff0000, v152
	v_lshlrev_b32_e32 v234, 16, v153
	v_and_b32_e32 v235, 0xffff0000, v153
	v_fma_f32 v106, v232, v106, v142
	v_fma_f32 v107, v233, v107, v143
	v_fma_f32 v108, v234, v108, v144
	v_fma_f32 v109, v235, v109, v145
	v_pk_fma_f32 v[228:229], v[106:107], v[106:107], v[228:229]
	s_nop 0
	v_pk_fma_f32 v[228:229], v[108:109], v[108:109], v[228:229]
	s_add_u32 s62, s22, 0x20000
	s_addc_u32 s63, s23, 0
	global_load_dwordx4 v[130:133], v200, s[62:63] nt
	global_load_dwordx4 v[134:137], v200, s[62:63] offset:16 nt
	global_load_dwordx4 v[138:141], v200, s[62:63] offset:512 nt
	global_load_dwordx4 v[142:145], v200, s[62:63] offset:528 nt
	s_add_u32 s64, s2, 0x4000
	s_addc_u32 s65, s3, 0
	global_load_dwordx4 v[146:149], v201, s[64:65]
	global_load_dwordx4 v[150:153], v201, s[64:65] offset:256
	s_nop 0
	v_add_f32_e32 v228, v228, v229
	ds_bpermute_b32 v229, v225, v228
	ds_bpermute_b32 v205, v226, v228
	ds_bpermute_b32 v164, v227, v228
	s_waitcnt lgkmcnt(0)
; #define NTL(p) __builtin_nontemporal_load((const f32x4*)(p))
; #define NTS(v, p) __builtin_nontemporal_store((v), (f32x4*)(p))
; __device__ __forceinline__ float bf_lo(unsigned w) { return __uint_as_float(w << 16); }
; __device__ __forceinline__ float bf_hi(unsigned w) { return __uint_as_float(w & 0xffff0000u); }
; __device__ __forceinline__ float sigmoidf_(float x) { return 1.0f / (1.0f + __expf(-x)); }
;     __device__ __forceinline__ void operator()(AccT& acc, const Unit& u, int wr, int wc, int fr, int fq) const {
;     ...
;         for (int r = 0; r < 8; ++r) { const int ai = r >> 2, m = r & 3; const int row = row0 + ai * 128 + m * 16;
;             if (r < 7) { const int rn = row0 + ((r + 1) >> 2) * 128 + ((r + 1) & 3) * 16; const float* hn = H + (size_t)rn * DM + col0; const bf16_t* pn = ppbase + (((r + 1) >> 2) * 128 + ((r + 1) & 3) * 16) * 256;
;                 hv[(r + 1) & 1][0] = NTL(hn); hv[(r + 1) & 1][1] = NTL(hn + 4); hv[(r + 1) & 1][2] = NTL(hn + 128); hv[(r + 1) & 1][3] = NTL(hn + 132);
;                 pv[(r + 1) & 1][0] = *(const u32x4*)pn; pv[(r + 1) & 1][1] = *(const u32x4*)(pn + 128); rs[(r + 1) & 1] = rss2[rn]; }
;             float* hp = H + (size_t)row * DM + col0; float ss = 0.f; const float rstd = rsqrtf(rs[r & 1] * (1.0f / DM) + 1e-6f);
; #pragma unroll
;             for (int bj = 0; bj < 2; ++bj) { const u32x4 pw = pv[r & 1][bj];
;                 const f32x4 b0 = *(const f32x4*)(bias + col0 + bj * 128), b1 = *(const f32x4*)(bias + col0 + bj * 128 + 4);
;                 const f32x4 p0 = (f32x4){bf_lo(pw.x), bf_hi(pw.x), bf_lo(pw.y), bf_hi(pw.y)}, p1 = (f32x4){bf_lo(pw.z), bf_hi(pw.z), bf_lo(pw.w), bf_hi(pw.w)};
;                 f32x4 g0 = acc[ai][bj][m][0] * rstd + b0, g1 = acc[ai][bj][m][1] * rstd + b1;
; #pragma unroll
;                 for (int j = 0; j < 4; ++j) { g0[j] = sigmoidf_(g0[j]); g1[j] = sigmoidf_(g1[j]); }
;                 const f32x4 v0 = hv[r & 1][2 * bj] + p0 * g0, v1 = hv[r & 1][2 * bj + 1] + p1 * g1;
;                 NTS(v0, hp + bj * 128); NTS(v1, hp + bj * 128 + 4);
; #pragma unroll
;                 for (int j = 0; j < 4; ++j) ss += v0[j] * v0[j] + v1[j] * v1[j]; }
;             ss += __shfl_xor(ss, 16); ss += __shfl_xor(ss, 32);
;             if (fq == 0) unsafeAtomicAdd(rss3 + row, ss); __builtin_amdgcn_sched_barrier(0); }
	v_add_f32_e32 v228, v228, v229
	v_add_f32_e32 v205, v205, v164
	v_add_f32_e32 v228, v228, v205
	s_mov_b64 s[66:67], exec
	s_and_b64 exec, exec, s[42:43]
	global_atomic_add_f32 v165, v202, v228, s[36:37] sc0
	s_mov_b64 exec, s[66:67]
	v_pk_mul_f32 v[126:127], v[126:127], v[206:207]
	v_pk_mul_f32 v[128:129], v[128:129], v[206:207]
	v_pk_mul_f32 v[118:119], v[118:119], v[206:207]
	v_pk_mul_f32 v[120:121], v[120:121], v[206:207]
	v_exp_f32_e32 v126, v126
	v_exp_f32_e32 v127, v127
	v_exp_f32_e32 v128, v128
	v_exp_f32_e32 v129, v129
	v_exp_f32_e32 v118, v118
	v_exp_f32_e32 v119, v119
	v_exp_f32_e32 v120, v120
	v_exp_f32_e32 v121, v121
	v_pk_add_f32 v[126:127], v[126:127], 1.0 op_sel_hi:[1,0]
	v_pk_add_f32 v[128:129], v[128:129], 1.0 op_sel_hi:[1,0]
	v_pk_add_f32 v[118:119], v[118:119], 1.0 op_sel_hi:[1,0]
	v_pk_add_f32 v[120:121], v[120:121], 1.0 op_sel_hi:[1,0]
	v_rcp_f32_e32 v240, v126
	v_rcp_f32_e32 v241, v127
	v_rcp_f32_e32 v242, v128
	v_rcp_f32_e32 v243, v129
	v_rcp_f32_e32 v244, v118
	v_rcp_f32_e32 v245, v119
	v_rcp_f32_e32 v246, v120
	v_rcp_f32_e32 v247, v121
	v_pk_fma_f32 v[126:127], v[126:127], v[240:241], 1.0 op_sel_hi:[1,1,0] neg_lo:[1,0,0] neg_hi:[1,0,0]
	v_pk_fma_f32 v[128:129], v[128:129], v[242:243], 1.0 op_sel_hi:[1,1,0] neg_lo:[1,0,0] neg_hi:[1,0,0]
	v_pk_fma_f32 v[118:119], v[118:119], v[244:245], 1.0 op_sel_hi:[1,1,0] neg_lo:[1,0,0] neg_hi:[1,0,0]
	v_pk_fma_f32 v[120:121], v[120:121], v[246:247], 1.0 op_sel_hi:[1,1,0] neg_lo:[1,0,0] neg_hi:[1,0,0]
	v_pk_fma_f32 v[126:127], v[126:127], v[240:241], v[240:241]
	v_pk_fma_f32 v[128:129], v[128:129], v[242:243], v[242:243]
	v_pk_fma_f32 v[118:119], v[118:119], v[244:245], v[244:245]
	v_pk_fma_f32 v[120:121], v[120:121], v[246:247], v[246:247]
	v_pk_mul_f32 v[102:103], v[102:103], v[206:207]
	v_pk_mul_f32 v[104:105], v[104:105], v[206:207]
	v_pk_mul_f32 v[98:99], v[98:99], v[206:207]
	v_pk_mul_f32 v[100:101], v[100:101], v[206:207]
	v_exp_f32_e32 v102, v102
	v_exp_f32_e32 v103, v103
	v_exp_f32_e32 v104, v104
	v_exp_f32_e32 v105, v105
	v_exp_f32_e32 v98, v98
	v_exp_f32_e32 v99, v99
	v_exp_f32_e32 v100, v100
	v_exp_f32_e32 v101, v101
	v_pk_add_f32 v[102:103], v[102:103], 1.0 op_sel_hi:[1,0]
	v_pk_add_f32 v[104:105], v[104:105], 1.0 op_sel_hi:[1,0]
	v_pk_add_f32 v[98:99], v[98:99], 1.0 op_sel_hi:[1,0]
	v_pk_add_f32 v[100:101], v[100:101], 1.0 op_sel_hi:[1,0]
	v_rcp_f32_e32 v240, v102
	v_rcp_f32_e32 v241, v103
	v_rcp_f32_e32 v242, v104
	v_rcp_f32_e32 v243, v105
	v_rcp_f32_e32 v244, v98
	v_rcp_f32_e32 v245, v99
	v_rcp_f32_e32 v246, v100
	v_rcp_f32_e32 v247, v101
	v_pk_fma_f32 v[102:103], v[102:103], v[240:241], 1.0 op_sel_hi:[1,1,0] neg_lo:[1,0,0] neg_hi:[1,0,0]
	v_pk_fma_f32 v[104:105], v[104:105], v[242:243], 1.0 op_sel_hi:[1,1,0] neg_lo:[1,0,0] neg_hi:[1,0,0]
	v_pk_fma_f32 v[98:99], v[98:99], v[244:245], 1.0 op_sel_hi:[1,1,0] neg_lo:[1,0,0] neg_hi:[1,0,0]
	v_pk_fma_f32 v[100:101], v[100:101], v[246:247], 1.0 op_sel_hi:[1,1,0] neg_lo:[1,0,0] neg_hi:[1,0,0]
	v_pk_fma_f32 v[102:103], v[102:103], v[240:241], v[240:241]
	v_pk_fma_f32 v[104:105], v[104:105], v[242:243], v[242:243]
	v_pk_fma_f32 v[98:99], v[98:99], v[244:245], v[244:245]
	v_pk_fma_f32 v[100:101], v[100:101], v[246:247], v[246:247]
	s_waitcnt vmcnt(7)
	v_lshlrev_b32_e32 v248, 16, v154
	v_and_b32_e32 v249, 0xffff0000, v154
	v_lshlrev_b32_e32 v250, 16, v155
	v_and_b32_e32 v251, 0xffff0000, v155
	v_fma_f32 v126, v248, v126, v184
	v_fma_f32 v127, v249, v127, v185
	v_fma_f32 v128, v250, v128, v186
	v_fma_f32 v129, v251, v129, v187
	v_pk_mul_f32 v[228:229], v[126:127], v[126:127]
	s_nop 0
	v_pk_fma_f32 v[228:229], v[128:129], v[128:129], v[228:229]
	v_lshlrev_b32_e32 v232, 16, v156
	v_and_b32_e32 v233, 0xffff0000, v156
	v_lshlrev_b32_e32 v234, 16, v157
	v_and_b32_e32 v235, 0xffff0000, v157
	v_fma_f32 v118, v232, v118, v188
	v_fma_f32 v119, v233, v119, v189
	v_fma_f32 v120, v234, v120, v190
	v_fma_f32 v121, v235, v121, v191
	v_pk_fma_f32 v[228:229], v[118:119], v[118:119], v[228:229]
	s_nop 0
	v_pk_fma_f32 v[228:229], v[120:121], v[120:121], v[228:229]
	v_lshlrev_b32_e32 v248, 16, v158
	v_and_b32_e32 v249, 0xffff0000, v158
	v_lshlrev_b32_e32 v250, 16, v159
	v_and_b32_e32 v251, 0xffff0000, v159
	v_fma_f32 v102, v248, v102, v192
	v_fma_f32 v103, v249, v103, v193
	v_fma_f32 v104, v250, v104, v194
	v_fma_f32 v105, v251, v105, v195
	v_pk_fma_f32 v[228:229], v[102:103], v[102:103], v[228:229]
	s_nop 0
	v_pk_fma_f32 v[228:229], v[104:105], v[104:105], v[228:229]
	v_lshlrev_b32_e32 v232, 16, v160
	v_and_b32_e32 v233, 0xffff0000, v160
	v_lshlrev_b32_e32 v234, 16, v161
	v_and_b32_e32 v235, 0xffff0000, v161
	v_fma_f32 v98, v232, v98, v196
	v_fma_f32 v99, v233, v99, v197
	v_fma_f32 v100, v234, v100, v198
	v_fma_f32 v101, v235, v101, v199
	v_pk_fma_f32 v[228:229], v[98:99], v[98:99], v[228:229]
	s_nop 0
	v_pk_fma_f32 v[228:229], v[100:101], v[100:101], v[228:229]
	s_add_u32 s62, s22, 0x30000
	s_addc_u32 s63, s23, 0
	global_load_dwordx4 v[184:187], v200, s[62:63] nt
	global_load_dwordx4 v[188:191], v200, s[62:63] offset:16 nt
	global_load_dwordx4 v[192:195], v200, s[62:63] offset:512 nt
	global_load_dwordx4 v[196:199], v200, s[62:63] offset:528 nt
	s_add_u32 s64, s2, 0x6000
	s_addc_u32 s65, s3, 0
	global_load_dwordx4 v[154:157], v201, s[64:65]
	global_load_dwordx4 v[158:161], v201, s[64:65] offset:256
	s_nop 0
	v_add_f32_e32 v228, v228, v229
	ds_bpermute_b32 v229, v225, v228
	ds_bpermute_b32 v205, v226, v228
	ds_bpermute_b32 v164, v227, v228
	s_waitcnt lgkmcnt(0)
; #define NTL(p) __builtin_nontemporal_load((const f32x4*)(p))
; #define NTS(v, p) __builtin_nontemporal_store((v), (f32x4*)(p))
; __device__ __forceinline__ float bf_lo(unsigned w) { return __uint_as_float(w << 16); }
; __device__ __forceinline__ float bf_hi(unsigned w) { return __uint_as_float(w & 0xffff0000u); }
; __device__ __forceinline__ float sigmoidf_(float x) { return 1.0f / (1.0f + __expf(-x)); }
;     __device__ __forceinline__ void operator()(AccT& acc, const Unit& u, int wr, int wc, int fr, int fq) const {
;     ...
;         for (int r = 0; r < 8; ++r) { const int ai = r >> 2, m = r & 3; const int row = row0 + ai * 128 + m * 16;
;             if (r < 7) { const int rn = row0 + ((r + 1) >> 2) * 128 + ((r + 1) & 3) * 16; const float* hn = H + (size_t)rn * DM + col0; const bf16_t* pn = ppbase + (((r + 1) >> 2) * 128 + ((r + 1) & 3) * 16) * 256;
;                 hv[(r + 1) & 1][0] = NTL(hn); hv[(r + 1) & 1][1] = NTL(hn + 4); hv[(r + 1) & 1][2] = NTL(hn + 128); hv[(r + 1) & 1][3] = NTL(hn + 132);
;                 pv[(r + 1) & 1][0] = *(const u32x4*)pn; pv[(r + 1) & 1][1] = *(const u32x4*)(pn + 128); rs[(r + 1) & 1] = rss2[rn]; }
;             float* hp = H + (size_t)row * DM + col0; float ss = 0.f; const float rstd = rsqrtf(rs[r & 1] * (1.0f / DM) + 1e-6f);
; #pragma unroll
;             for (int bj = 0; bj < 2; ++bj) { const u32x4 pw = pv[r & 1][bj];
;                 const f32x4 b0 = *(const f32x4*)(bias + col0 + bj * 128), b1 = *(const f32x4*)(bias + col0 + bj * 128 + 4);
;                 const f32x4 p0 = (f32x4){bf_lo(pw.x), bf_hi(pw.x), bf_lo(pw.y), bf_hi(pw.y)}, p1 = (f32x4){bf_lo(pw.z), bf_hi(pw.z), bf_lo(pw.w), bf_hi(pw.w)};
;                 f32x4 g0 = acc[ai][bj][m][0] * rstd + b0, g1 = acc[ai][bj][m][1] * rstd + b1;
; #pragma unroll
;                 for (int j = 0; j < 4; ++j) { g0[j] = sigmoidf_(g0[j]); g1[j] = sigmoidf_(g1[j]); }
;                 const f32x4 v0 = hv[r & 1][2 * bj] + p0 * g0, v1 = hv[r & 1][2 * bj + 1] + p1 * g1;
;                 NTS(v0, hp + bj * 128); NTS(v1, hp + bj * 128 + 4);
; #pragma unroll
;                 for (int j = 0; j < 4; ++j) ss += v0[j] * v0[j] + v1[j] * v1[j]; }
;             ss += __shfl_xor(ss, 16); ss += __shfl_xor(ss, 32);
;             if (fq == 0) unsafeAtomicAdd(rss3 + row, ss); __builtin_amdgcn_sched_barrier(0); }
	v_add_f32_e32 v228, v228, v229
	v_add_f32_e32 v205, v205, v164
	v_add_f32_e32 v228, v228, v205
	s_mov_b64 s[66:67], exec
	s_and_b64 exec, exec, s[42:43]
	global_atomic_add_f32 v165, v202, v228, s[36:37] offset:64 sc0
	s_mov_b64 exec, s[66:67]
	v_pk_mul_f32 v[94:95], v[94:95], v[206:207]
	v_pk_mul_f32 v[96:97], v[96:97], v[206:207]
	v_pk_mul_f32 v[90:91], v[90:91], v[206:207]
	v_pk_mul_f32 v[92:93], v[92:93], v[206:207]
	v_exp_f32_e32 v94, v94
	v_exp_f32_e32 v95, v95
	v_exp_f32_e32 v96, v96
	v_exp_f32_e32 v97, v97
	v_exp_f32_e32 v90, v90
	v_exp_f32_e32 v91, v91
	v_exp_f32_e32 v92, v92
	v_exp_f32_e32 v93, v93
	v_pk_add_f32 v[94:95], v[94:95], 1.0 op_sel_hi:[1,0]
	v_pk_add_f32 v[96:97], v[96:97], 1.0 op_sel_hi:[1,0]
	v_pk_add_f32 v[90:91], v[90:91], 1.0 op_sel_hi:[1,0]
	v_pk_add_f32 v[92:93], v[92:93], 1.0 op_sel_hi:[1,0]
	v_rcp_f32_e32 v240, v94
	v_rcp_f32_e32 v241, v95
	v_rcp_f32_e32 v242, v96
	v_rcp_f32_e32 v243, v97
	v_rcp_f32_e32 v244, v90
	v_rcp_f32_e32 v245, v91
	v_rcp_f32_e32 v246, v92
	v_rcp_f32_e32 v247, v93
	v_pk_fma_f32 v[94:95], v[94:95], v[240:241], 1.0 op_sel_hi:[1,1,0] neg_lo:[1,0,0] neg_hi:[1,0,0]
	v_pk_fma_f32 v[96:97], v[96:97], v[242:243], 1.0 op_sel_hi:[1,1,0] neg_lo:[1,0,0] neg_hi:[1,0,0]
	v_pk_fma_f32 v[90:91], v[90:91], v[244:245], 1.0 op_sel_hi:[1,1,0] neg_lo:[1,0,0] neg_hi:[1,0,0]
	v_pk_fma_f32 v[92:93], v[92:93], v[246:247], 1.0 op_sel_hi:[1,1,0] neg_lo:[1,0,0] neg_hi:[1,0,0]
	v_pk_fma_f32 v[94:95], v[94:95], v[240:241], v[240:241]
	v_pk_fma_f32 v[96:97], v[96:97], v[242:243], v[242:243]
	v_pk_fma_f32 v[90:91], v[90:91], v[244:245], v[244:245]
	v_pk_fma_f32 v[92:93], v[92:93], v[246:247], v[246:247]
	v_pk_mul_f32 v[86:87], v[86:87], v[206:207]
	v_pk_mul_f32 v[88:89], v[88:89], v[206:207]
	v_pk_mul_f32 v[82:83], v[82:83], v[206:207]
	v_pk_mul_f32 v[84:85], v[84:85], v[206:207]
	v_exp_f32_e32 v86, v86
	v_exp_f32_e32 v87, v87
	v_exp_f32_e32 v88, v88
	v_exp_f32_e32 v89, v89
	v_exp_f32_e32 v82, v82
	v_exp_f32_e32 v83, v83
	v_exp_f32_e32 v84, v84
	v_exp_f32_e32 v85, v85
	v_pk_add_f32 v[86:87], v[86:87], 1.0 op_sel_hi:[1,0]
	v_pk_add_f32 v[88:89], v[88:89], 1.0 op_sel_hi:[1,0]
	v_pk_add_f32 v[82:83], v[82:83], 1.0 op_sel_hi:[1,0]
	v_pk_add_f32 v[84:85], v[84:85], 1.0 op_sel_hi:[1,0]
	v_rcp_f32_e32 v240, v86
	v_rcp_f32_e32 v241, v87
	v_rcp_f32_e32 v242, v88
	v_rcp_f32_e32 v243, v89
	v_rcp_f32_e32 v244, v82
	v_rcp_f32_e32 v245, v83
	v_rcp_f32_e32 v246, v84
	v_rcp_f32_e32 v247, v85
	v_pk_fma_f32 v[86:87], v[86:87], v[240:241], 1.0 op_sel_hi:[1,1,0] neg_lo:[1,0,0] neg_hi:[1,0,0]
	v_pk_fma_f32 v[88:89], v[88:89], v[242:243], 1.0 op_sel_hi:[1,1,0] neg_lo:[1,0,0] neg_hi:[1,0,0]
	v_pk_fma_f32 v[82:83], v[82:83], v[244:245], 1.0 op_sel_hi:[1,1,0] neg_lo:[1,0,0] neg_hi:[1,0,0]
	v_pk_fma_f32 v[84:85], v[84:85], v[246:247], 1.0 op_sel_hi:[1,1,0] neg_lo:[1,0,0] neg_hi:[1,0,0]
	v_pk_fma_f32 v[86:87], v[86:87], v[240:241], v[240:241]
	v_pk_fma_f32 v[88:89], v[88:89], v[242:243], v[242:243]
	v_pk_fma_f32 v[82:83], v[82:83], v[244:245], v[244:245]
	v_pk_fma_f32 v[84:85], v[84:85], v[246:247], v[246:247]
	s_waitcnt vmcnt(8)
	v_lshlrev_b32_e32 v248, 16, v146
	v_and_b32_e32 v249, 0xffff0000, v146
	v_lshlrev_b32_e32 v250, 16, v147
	v_and_b32_e32 v251, 0xffff0000, v147
	v_fma_f32 v94, v248, v94, v130
	v_fma_f32 v95, v249, v95, v131
	v_fma_f32 v96, v250, v96, v132
	v_fma_f32 v97, v251, v97, v133
	v_pk_mul_f32 v[228:229], v[94:95], v[94:95]
	s_nop 0
	v_pk_fma_f32 v[228:229], v[96:97], v[96:97], v[228:229]
	v_lshlrev_b32_e32 v232, 16, v148
	v_and_b32_e32 v233, 0xffff0000, v148
	v_lshlrev_b32_e32 v234, 16, v149
	v_and_b32_e32 v235, 0xffff0000, v149
	v_fma_f32 v90, v232, v90, v134
	v_fma_f32 v91, v233, v91, v135
	v_fma_f32 v92, v234, v92, v136
	v_fma_f32 v93, v235, v93, v137
	v_pk_fma_f32 v[228:229], v[90:91], v[90:91], v[228:229]
	s_nop 0
	v_pk_fma_f32 v[228:229], v[92:93], v[92:93], v[228:229]
	v_lshlrev_b32_e32 v248, 16, v150
	v_and_b32_e32 v249, 0xffff0000, v150
	v_lshlrev_b32_e32 v250, 16, v151
	v_and_b32_e32 v251, 0xffff0000, v151
	v_fma_f32 v86, v248, v86, v138
	v_fma_f32 v87, v249, v87, v139
	v_fma_f32 v88, v250, v88, v140
	v_fma_f32 v89, v251, v89, v141
	v_pk_fma_f32 v[228:229], v[86:87], v[86:87], v[228:229]
	s_nop 0
	v_pk_fma_f32 v[228:229], v[88:89], v[88:89], v[228:229]
	v_lshlrev_b32_e32 v232, 16, v152
	v_and_b32_e32 v233, 0xffff0000, v152
	v_lshlrev_b32_e32 v234, 16, v153
	v_and_b32_e32 v235, 0xffff0000, v153
	v_fma_f32 v82, v232, v82, v142
	v_fma_f32 v83, v233, v83, v143
	v_fma_f32 v84, v234, v84, v144
	v_fma_f32 v85, v235, v85, v145
	v_pk_fma_f32 v[228:229], v[82:83], v[82:83], v[228:229]
	s_nop 0
	v_pk_fma_f32 v[228:229], v[84:85], v[84:85], v[228:229]
	s_add_u32 s62, s22, 0x80000
	s_addc_u32 s63, s23, 0
	global_load_dwordx4 v[130:133], v200, s[62:63] nt
	global_load_dwordx4 v[134:137], v200, s[62:63] offset:16 nt
	global_load_dwordx4 v[138:141], v200, s[62:63] offset:512 nt
	global_load_dwordx4 v[142:145], v200, s[62:63] offset:528 nt
	s_add_u32 s64, s2, 0x10000
	s_addc_u32 s65, s3, 0
	global_load_dwordx4 v[146:149], v201, s[64:65]
	global_load_dwordx4 v[150:153], v201, s[64:65] offset:256
	s_nop 0
	v_add_f32_e32 v228, v228, v229
	ds_bpermute_b32 v229, v225, v228
	ds_bpermute_b32 v205, v226, v228
	ds_bpermute_b32 v164, v227, v228
	s_waitcnt lgkmcnt(0)
; #define NTL(p) __builtin_nontemporal_load((const f32x4*)(p))
; #define NTS(v, p) __builtin_nontemporal_store((v), (f32x4*)(p))
; __device__ __forceinline__ float bf_lo(unsigned w) { return __uint_as_float(w << 16); }
; __device__ __forceinline__ float bf_hi(unsigned w) { return __uint_as_float(w & 0xffff0000u); }
; __device__ __forceinline__ float sigmoidf_(float x) { return 1.0f / (1.0f + __expf(-x)); }
;     __device__ __forceinline__ void operator()(AccT& acc, const Unit& u, int wr, int wc, int fr, int fq) const {
;     ...
;         for (int r = 0; r < 8; ++r) { const int ai = r >> 2, m = r & 3; const int row = row0 + ai * 128 + m * 16;
;             if (r < 7) { const int rn = row0 + ((r + 1) >> 2) * 128 + ((r + 1) & 3) * 16; const float* hn = H + (size_t)rn * DM + col0; const bf16_t* pn = ppbase + (((r + 1) >> 2) * 128 + ((r + 1) & 3) * 16) * 256;
;                 hv[(r + 1) & 1][0] = NTL(hn); hv[(r + 1) & 1][1] = NTL(hn + 4); hv[(r + 1) & 1][2] = NTL(hn + 128); hv[(r + 1) & 1][3] = NTL(hn + 132);
;                 pv[(r + 1) & 1][0] = *(const u32x4*)pn; pv[(r + 1) & 1][1] = *(const u32x4*)(pn + 128); rs[(r + 1) & 1] = rss2[rn]; }
;             float* hp = H + (size_t)row * DM + col0; float ss = 0.f; const float rstd = rsqrtf(rs[r & 1] * (1.0f / DM) + 1e-6f);
; #pragma unroll
;             for (int bj = 0; bj < 2; ++bj) { const u32x4 pw = pv[r & 1][bj];
;                 const f32x4 b0 = *(const f32x4*)(bias + col0 + bj * 128), b1 = *(const f32x4*)(bias + col0 + bj * 128 + 4);
;                 const f32x4 p0 = (f32x4){bf_lo(pw.x), bf_hi(pw.x), bf_lo(pw.y), bf_hi(pw.y)}, p1 = (f32x4){bf_lo(pw.z), bf_hi(pw.z), bf_lo(pw.w), bf_hi(pw.w)};
;                 f32x4 g0 = acc[ai][bj][m][0] * rstd + b0, g1 = acc[ai][bj][m][1] * rstd + b1;
; #pragma unroll
;                 for (int j = 0; j < 4; ++j) { g0[j] = sigmoidf_(g0[j]); g1[j] = sigmoidf_(g1[j]); }
;                 const f32x4 v0 = hv[r & 1][2 * bj] + p0 * g0, v1 = hv[r & 1][2 * bj + 1] + p1 * g1;
;                 NTS(v0, hp + bj * 128); NTS(v1, hp + bj * 128 + 4);
; #pragma unroll
;                 for (int j = 0; j < 4; ++j) ss += v0[j] * v0[j] + v1[j] * v1[j]; }
;             ss += __shfl_xor(ss, 16); ss += __shfl_xor(ss, 32);
;             if (fq == 0) unsafeAtomicAdd(rss3 + row, ss); __builtin_amdgcn_sched_barrier(0); }
	v_add_f32_e32 v228, v228, v229
	v_add_f32_e32 v205, v205, v164
	v_add_f32_e32 v228, v228, v205
	s_mov_b64 s[66:67], exec
	s_and_b64 exec, exec, s[42:43]
	global_atomic_add_f32 v165, v202, v228, s[36:37] offset:128 sc0
	s_mov_b64 exec, s[66:67]
	v_pk_mul_f32 v[78:79], v[78:79], v[206:207]
	v_pk_mul_f32 v[80:81], v[80:81], v[206:207]
	v_pk_mul_f32 v[74:75], v[74:75], v[206:207]
	v_pk_mul_f32 v[76:77], v[76:77], v[206:207]
	v_exp_f32_e32 v78, v78
	v_exp_f32_e32 v79, v79
	v_exp_f32_e32 v80, v80
	v_exp_f32_e32 v81, v81
	v_exp_f32_e32 v74, v74
	v_exp_f32_e32 v75, v75
	v_exp_f32_e32 v76, v76
	v_exp_f32_e32 v77, v77
	v_pk_add_f32 v[78:79], v[78:79], 1.0 op_sel_hi:[1,0]
	v_pk_add_f32 v[80:81], v[80:81], 1.0 op_sel_hi:[1,0]
	v_pk_add_f32 v[74:75], v[74:75], 1.0 op_sel_hi:[1,0]
	v_pk_add_f32 v[76:77], v[76:77], 1.0 op_sel_hi:[1,0]
	v_rcp_f32_e32 v240, v78
	v_rcp_f32_e32 v241, v79
	v_rcp_f32_e32 v242, v80
	v_rcp_f32_e32 v243, v81
	v_rcp_f32_e32 v244, v74
	v_rcp_f32_e32 v245, v75
	v_rcp_f32_e32 v246, v76
	v_rcp_f32_e32 v247, v77
	v_pk_fma_f32 v[78:79], v[78:79], v[240:241], 1.0 op_sel_hi:[1,1,0] neg_lo:[1,0,0] neg_hi:[1,0,0]
	v_pk_fma_f32 v[80:81], v[80:81], v[242:243], 1.0 op_sel_hi:[1,1,0] neg_lo:[1,0,0] neg_hi:[1,0,0]
	v_pk_fma_f32 v[74:75], v[74:75], v[244:245], 1.0 op_sel_hi:[1,1,0] neg_lo:[1,0,0] neg_hi:[1,0,0]
	v_pk_fma_f32 v[76:77], v[76:77], v[246:247], 1.0 op_sel_hi:[1,1,0] neg_lo:[1,0,0] neg_hi:[1,0,0]
	v_pk_fma_f32 v[78:79], v[78:79], v[240:241], v[240:241]
	v_pk_fma_f32 v[80:81], v[80:81], v[242:243], v[242:243]
	v_pk_fma_f32 v[74:75], v[74:75], v[244:245], v[244:245]
	v_pk_fma_f32 v[76:77], v[76:77], v[246:247], v[246:247]
	v_pk_mul_f32 v[70:71], v[70:71], v[206:207]
	v_pk_mul_f32 v[72:73], v[72:73], v[206:207]
	v_pk_mul_f32 v[66:67], v[66:67], v[206:207]
	v_pk_mul_f32 v[68:69], v[68:69], v[206:207]
	v_exp_f32_e32 v70, v70
	v_exp_f32_e32 v71, v71
	v_exp_f32_e32 v72, v72
	v_exp_f32_e32 v73, v73
	v_exp_f32_e32 v66, v66
	v_exp_f32_e32 v67, v67
	v_exp_f32_e32 v68, v68
	v_exp_f32_e32 v69, v69
	v_pk_add_f32 v[70:71], v[70:71], 1.0 op_sel_hi:[1,0]
	v_pk_add_f32 v[72:73], v[72:73], 1.0 op_sel_hi:[1,0]
	v_pk_add_f32 v[66:67], v[66:67], 1.0 op_sel_hi:[1,0]
	v_pk_add_f32 v[68:69], v[68:69], 1.0 op_sel_hi:[1,0]
	v_rcp_f32_e32 v240, v70
	v_rcp_f32_e32 v241, v71
	v_rcp_f32_e32 v242, v72
	v_rcp_f32_e32 v243, v73
	v_rcp_f32_e32 v244, v66
	v_rcp_f32_e32 v245, v67
	v_rcp_f32_e32 v246, v68
	v_rcp_f32_e32 v247, v69
	v_pk_fma_f32 v[70:71], v[70:71], v[240:241], 1.0 op_sel_hi:[1,1,0] neg_lo:[1,0,0] neg_hi:[1,0,0]
	v_pk_fma_f32 v[72:73], v[72:73], v[242:243], 1.0 op_sel_hi:[1,1,0] neg_lo:[1,0,0] neg_hi:[1,0,0]
	v_pk_fma_f32 v[66:67], v[66:67], v[244:245], 1.0 op_sel_hi:[1,1,0] neg_lo:[1,0,0] neg_hi:[1,0,0]
	v_pk_fma_f32 v[68:69], v[68:69], v[246:247], 1.0 op_sel_hi:[1,1,0] neg_lo:[1,0,0] neg_hi:[1,0,0]
	v_pk_fma_f32 v[70:71], v[70:71], v[240:241], v[240:241]
	v_pk_fma_f32 v[72:73], v[72:73], v[242:243], v[242:243]
	v_pk_fma_f32 v[66:67], v[66:67], v[244:245], v[244:245]
	v_pk_fma_f32 v[68:69], v[68:69], v[246:247], v[246:247]
	s_waitcnt vmcnt(8)
	v_lshlrev_b32_e32 v248, 16, v154
	v_and_b32_e32 v249, 0xffff0000, v154
	v_lshlrev_b32_e32 v250, 16, v155
	v_and_b32_e32 v251, 0xffff0000, v155
	v_fma_f32 v78, v248, v78, v184
	v_fma_f32 v79, v249, v79, v185
	v_fma_f32 v80, v250, v80, v186
	v_fma_f32 v81, v251, v81, v187
	v_pk_mul_f32 v[228:229], v[78:79], v[78:79]
	s_nop 0
	v_pk_fma_f32 v[228:229], v[80:81], v[80:81], v[228:229]
	v_lshlrev_b32_e32 v232, 16, v156
	v_and_b32_e32 v233, 0xffff0000, v156
	v_lshlrev_b32_e32 v234, 16, v157
	v_and_b32_e32 v235, 0xffff0000, v157
	v_fma_f32 v74, v232, v74, v188
	v_fma_f32 v75, v233, v75, v189
	v_fma_f32 v76, v234, v76, v190
	v_fma_f32 v77, v235, v77, v191
	v_pk_fma_f32 v[228:229], v[74:75], v[74:75], v[228:229]
	s_nop 0
	v_pk_fma_f32 v[228:229], v[76:77], v[76:77], v[228:229]
	v_lshlrev_b32_e32 v248, 16, v158
	v_and_b32_e32 v249, 0xffff0000, v158
	v_lshlrev_b32_e32 v250, 16, v159
	v_and_b32_e32 v251, 0xffff0000, v159
	v_fma_f32 v70, v248, v70, v192
	v_fma_f32 v71, v249, v71, v193
	v_fma_f32 v72, v250, v72, v194
	v_fma_f32 v73, v251, v73, v195
	v_pk_fma_f32 v[228:229], v[70:71], v[70:71], v[228:229]
	s_nop 0
	v_pk_fma_f32 v[228:229], v[72:73], v[72:73], v[228:229]
	v_lshlrev_b32_e32 v232, 16, v160
	v_and_b32_e32 v233, 0xffff0000, v160
	v_lshlrev_b32_e32 v234, 16, v161
	v_and_b32_e32 v235, 0xffff0000, v161
	v_fma_f32 v66, v232, v66, v196
	v_fma_f32 v67, v233, v67, v197
	v_fma_f32 v68, v234, v68, v198
	v_fma_f32 v69, v235, v69, v199
	v_pk_fma_f32 v[228:229], v[66:67], v[66:67], v[228:229]
	s_nop 0
	v_pk_fma_f32 v[228:229], v[68:69], v[68:69], v[228:229]
	s_add_u32 s62, s22, 0x90000
	s_addc_u32 s63, s23, 0
	global_load_dwordx4 v[184:187], v200, s[62:63] nt
	global_load_dwordx4 v[188:191], v200, s[62:63] offset:16 nt
	global_load_dwordx4 v[192:195], v200, s[62:63] offset:512 nt
	global_load_dwordx4 v[196:199], v200, s[62:63] offset:528 nt
	s_add_u32 s64, s2, 0x12000
	s_addc_u32 s65, s3, 0
	global_load_dwordx4 v[154:157], v201, s[64:65]
	global_load_dwordx4 v[158:161], v201, s[64:65] offset:256
	s_nop 0
	v_add_f32_e32 v228, v228, v229
	ds_bpermute_b32 v229, v225, v228
	ds_bpermute_b32 v205, v226, v228
	ds_bpermute_b32 v164, v227, v228
	s_waitcnt lgkmcnt(0)
; #define NTL(p) __builtin_nontemporal_load((const f32x4*)(p))
; #define NTS(v, p) __builtin_nontemporal_store((v), (f32x4*)(p))
; __device__ __forceinline__ float bf_lo(unsigned w) { return __uint_as_float(w << 16); }
; __device__ __forceinline__ float bf_hi(unsigned w) { return __uint_as_float(w & 0xffff0000u); }
; __device__ __forceinline__ float sigmoidf_(float x) { return 1.0f / (1.0f + __expf(-x)); }
;     __device__ __forceinline__ void operator()(AccT& acc, const Unit& u, int wr, int wc, int fr, int fq) const {
;     ...
;         for (int r = 0; r < 8; ++r) { const int ai = r >> 2, m = r & 3; const int row = row0 + ai * 128 + m * 16;
;             if (r < 7) { const int rn = row0 + ((r + 1) >> 2) * 128 + ((r + 1) & 3) * 16; const float* hn = H + (size_t)rn * DM + col0; const bf16_t* pn = ppbase + (((r + 1) >> 2) * 128 + ((r + 1) & 3) * 16) * 256;
;                 hv[(r + 1) & 1][0] = NTL(hn); hv[(r + 1) & 1][1] = NTL(hn + 4); hv[(r + 1) & 1][2] = NTL(hn + 128); hv[(r + 1) & 1][3] = NTL(hn + 132);
;                 pv[(r + 1) & 1][0] = *(const u32x4*)pn; pv[(r + 1) & 1][1] = *(const u32x4*)(pn + 128); rs[(r + 1) & 1] = rss2[rn]; }
;             float* hp = H + (size_t)row * DM + col0; float ss = 0.f; const float rstd = rsqrtf(rs[r & 1] * (1.0f / DM) + 1e-6f);
; #pragma unroll
;             for (int bj = 0; bj < 2; ++bj) { const u32x4 pw = pv[r & 1][bj];
;                 const f32x4 b0 = *(const f32x4*)(bias + col0 + bj * 128), b1 = *(const f32x4*)(bias + col0 + bj * 128 + 4);
;                 const f32x4 p0 = (f32x4){bf_lo(pw.x), bf_hi(pw.x), bf_lo(pw.y), bf_hi(pw.y)}, p1 = (f32x4){bf_lo(pw.z), bf_hi(pw.z), bf_lo(pw.w), bf_hi(pw.w)};
;                 f32x4 g0 = acc[ai][bj][m][0] * rstd + b0, g1 = acc[ai][bj][m][1] * rstd + b1;
; #pragma unroll
;                 for (int j = 0; j < 4; ++j) { g0[j] = sigmoidf_(g0[j]); g1[j] = sigmoidf_(g1[j]); }
;                 const f32x4 v0 = hv[r & 1][2 * bj] + p0 * g0, v1 = hv[r & 1][2 * bj + 1] + p1 * g1;
;                 NTS(v0, hp + bj * 128); NTS(v1, hp + bj * 128 + 4);
; #pragma unroll
;                 for (int j = 0; j < 4; ++j) ss += v0[j] * v0[j] + v1[j] * v1[j]; }
;             ss += __shfl_xor(ss, 16); ss += __shfl_xor(ss, 32);
;             if (fq == 0) unsafeAtomicAdd(rss3 + row, ss); __builtin_amdgcn_sched_barrier(0); }
	v_add_f32_e32 v228, v228, v229
	v_add_f32_e32 v205, v205, v164
	v_add_f32_e32 v228, v228, v205
	s_mov_b64 s[66:67], exec
	s_and_b64 exec, exec, s[42:43]
	global_atomic_add_f32 v165, v202, v228, s[36:37] offset:192 sc0
	s_mov_b64 exec, s[66:67]
	v_pk_mul_f32 v[62:63], v[62:63], v[206:207]
	v_pk_mul_f32 v[64:65], v[64:65], v[206:207]
	v_pk_mul_f32 v[58:59], v[58:59], v[206:207]
	v_pk_mul_f32 v[60:61], v[60:61], v[206:207]
	v_exp_f32_e32 v62, v62
	v_exp_f32_e32 v63, v63
	v_exp_f32_e32 v64, v64
	v_exp_f32_e32 v65, v65
	v_exp_f32_e32 v58, v58
	v_exp_f32_e32 v59, v59
	v_exp_f32_e32 v60, v60
	v_exp_f32_e32 v61, v61
	v_pk_add_f32 v[62:63], v[62:63], 1.0 op_sel_hi:[1,0]
	v_pk_add_f32 v[64:65], v[64:65], 1.0 op_sel_hi:[1,0]
	v_pk_add_f32 v[58:59], v[58:59], 1.0 op_sel_hi:[1,0]
	v_pk_add_f32 v[60:61], v[60:61], 1.0 op_sel_hi:[1,0]
	v_rcp_f32_e32 v240, v62
	v_rcp_f32_e32 v241, v63
	v_rcp_f32_e32 v242, v64
	v_rcp_f32_e32 v243, v65
	v_rcp_f32_e32 v244, v58
	v_rcp_f32_e32 v245, v59
	v_rcp_f32_e32 v246, v60
	v_rcp_f32_e32 v247, v61
	v_pk_fma_f32 v[62:63], v[62:63], v[240:241], 1.0 op_sel_hi:[1,1,0] neg_lo:[1,0,0] neg_hi:[1,0,0]
	v_pk_fma_f32 v[64:65], v[64:65], v[242:243], 1.0 op_sel_hi:[1,1,0] neg_lo:[1,0,0] neg_hi:[1,0,0]
	v_pk_fma_f32 v[58:59], v[58:59], v[244:245], 1.0 op_sel_hi:[1,1,0] neg_lo:[1,0,0] neg_hi:[1,0,0]
	v_pk_fma_f32 v[60:61], v[60:61], v[246:247], 1.0 op_sel_hi:[1,1,0] neg_lo:[1,0,0] neg_hi:[1,0,0]
	v_pk_fma_f32 v[62:63], v[62:63], v[240:241], v[240:241]
	v_pk_fma_f32 v[64:65], v[64:65], v[242:243], v[242:243]
	v_pk_fma_f32 v[58:59], v[58:59], v[244:245], v[244:245]
	v_pk_fma_f32 v[60:61], v[60:61], v[246:247], v[246:247]
	v_pk_mul_f32 v[54:55], v[54:55], v[206:207]
	v_pk_mul_f32 v[56:57], v[56:57], v[206:207]
	v_pk_mul_f32 v[50:51], v[50:51], v[206:207]
	v_pk_mul_f32 v[52:53], v[52:53], v[206:207]
	v_exp_f32_e32 v54, v54
	v_exp_f32_e32 v55, v55
	v_exp_f32_e32 v56, v56
	v_exp_f32_e32 v57, v57
	v_exp_f32_e32 v50, v50
	v_exp_f32_e32 v51, v51
	v_exp_f32_e32 v52, v52
	v_exp_f32_e32 v53, v53
	v_pk_add_f32 v[54:55], v[54:55], 1.0 op_sel_hi:[1,0]
	v_pk_add_f32 v[56:57], v[56:57], 1.0 op_sel_hi:[1,0]
	v_pk_add_f32 v[50:51], v[50:51], 1.0 op_sel_hi:[1,0]
	v_pk_add_f32 v[52:53], v[52:53], 1.0 op_sel_hi:[1,0]
	v_rcp_f32_e32 v240, v54
	v_rcp_f32_e32 v241, v55
	v_rcp_f32_e32 v242, v56
	v_rcp_f32_e32 v243, v57
	v_rcp_f32_e32 v244, v50
	v_rcp_f32_e32 v245, v51
	v_rcp_f32_e32 v246, v52
	v_rcp_f32_e32 v247, v53
	v_pk_fma_f32 v[54:55], v[54:55], v[240:241], 1.0 op_sel_hi:[1,1,0] neg_lo:[1,0,0] neg_hi:[1,0,0]
	v_pk_fma_f32 v[56:57], v[56:57], v[242:243], 1.0 op_sel_hi:[1,1,0] neg_lo:[1,0,0] neg_hi:[1,0,0]
	v_pk_fma_f32 v[50:51], v[50:51], v[244:245], 1.0 op_sel_hi:[1,1,0] neg_lo:[1,0,0] neg_hi:[1,0,0]
	v_pk_fma_f32 v[52:53], v[52:53], v[246:247], 1.0 op_sel_hi:[1,1,0] neg_lo:[1,0,0] neg_hi:[1,0,0]
	v_pk_fma_f32 v[54:55], v[54:55], v[240:241], v[240:241]
	v_pk_fma_f32 v[56:57], v[56:57], v[242:243], v[242:243]
	v_pk_fma_f32 v[50:51], v[50:51], v[244:245], v[244:245]
	v_pk_fma_f32 v[52:53], v[52:53], v[246:247], v[246:247]
	s_waitcnt vmcnt(8)
	v_lshlrev_b32_e32 v248, 16, v146
	v_and_b32_e32 v249, 0xffff0000, v146
	v_lshlrev_b32_e32 v250, 16, v147
	v_and_b32_e32 v251, 0xffff0000, v147
	v_fma_f32 v62, v248, v62, v130
	v_fma_f32 v63, v249, v63, v131
	v_fma_f32 v64, v250, v64, v132
	v_fma_f32 v65, v251, v65, v133
	v_pk_mul_f32 v[228:229], v[62:63], v[62:63]
	s_nop 0
	v_pk_fma_f32 v[228:229], v[64:65], v[64:65], v[228:229]
	v_lshlrev_b32_e32 v232, 16, v148
	v_and_b32_e32 v233, 0xffff0000, v148
	v_lshlrev_b32_e32 v234, 16, v149
	v_and_b32_e32 v235, 0xffff0000, v149
	v_fma_f32 v58, v232, v58, v134
	v_fma_f32 v59, v233, v59, v135
	v_fma_f32 v60, v234, v60, v136
	v_fma_f32 v61, v235, v61, v137
	v_pk_fma_f32 v[228:229], v[58:59], v[58:59], v[228:229]
	s_nop 0
	v_pk_fma_f32 v[228:229], v[60:61], v[60:61], v[228:229]
	v_lshlrev_b32_e32 v248, 16, v150
	v_and_b32_e32 v249, 0xffff0000, v150
	v_lshlrev_b32_e32 v250, 16, v151
	v_and_b32_e32 v251, 0xffff0000, v151
	v_fma_f32 v54, v248, v54, v138
	v_fma_f32 v55, v249, v55, v139
	v_fma_f32 v56, v250, v56, v140
	v_fma_f32 v57, v251, v57, v141
	v_pk_fma_f32 v[228:229], v[54:55], v[54:55], v[228:229]
	s_nop 0
	v_pk_fma_f32 v[228:229], v[56:57], v[56:57], v[228:229]
	v_lshlrev_b32_e32 v232, 16, v152
	v_and_b32_e32 v233, 0xffff0000, v152
	v_lshlrev_b32_e32 v234, 16, v153
	v_and_b32_e32 v235, 0xffff0000, v153
	v_fma_f32 v50, v232, v50, v142
	v_fma_f32 v51, v233, v51, v143
	v_fma_f32 v52, v234, v52, v144
	v_fma_f32 v53, v235, v53, v145
	v_pk_fma_f32 v[228:229], v[50:51], v[50:51], v[228:229]
	s_nop 0
	v_pk_fma_f32 v[228:229], v[52:53], v[52:53], v[228:229]
	s_add_u32 s62, s22, 0xa0000
	s_addc_u32 s63, s23, 0
	global_load_dwordx4 v[130:133], v200, s[62:63] nt
	global_load_dwordx4 v[134:137], v200, s[62:63] offset:16 nt
	global_load_dwordx4 v[138:141], v200, s[62:63] offset:512 nt
	global_load_dwordx4 v[142:145], v200, s[62:63] offset:528 nt
	s_add_u32 s64, s2, 0x14000
	s_addc_u32 s65, s3, 0
	global_load_dwordx4 v[146:149], v201, s[64:65]
	global_load_dwordx4 v[150:153], v201, s[64:65] offset:256
	s_nop 0
	v_add_f32_e32 v228, v228, v229
	ds_bpermute_b32 v229, v225, v228
	ds_bpermute_b32 v205, v226, v228
	ds_bpermute_b32 v164, v227, v228
	s_waitcnt lgkmcnt(0)
; #define NTL(p) __builtin_nontemporal_load((const f32x4*)(p))
; #define NTS(v, p) __builtin_nontemporal_store((v), (f32x4*)(p))
; __device__ __forceinline__ float bf_lo(unsigned w) { return __uint_as_float(w << 16); }
; __device__ __forceinline__ float bf_hi(unsigned w) { return __uint_as_float(w & 0xffff0000u); }
; __device__ __forceinline__ float sigmoidf_(float x) { return 1.0f / (1.0f + __expf(-x)); }
;     __device__ __forceinline__ void operator()(AccT& acc, const Unit& u, int wr, int wc, int fr, int fq) const {
;     ...
;         for (int r = 0; r < 8; ++r) { const int ai = r >> 2, m = r & 3; const int row = row0 + ai * 128 + m * 16;
;             if (r < 7) { const int rn = row0 + ((r + 1) >> 2) * 128 + ((r + 1) & 3) * 16; const float* hn = H + (size_t)rn * DM + col0; const bf16_t* pn = ppbase + (((r + 1) >> 2) * 128 + ((r + 1) & 3) * 16) * 256;
;                 hv[(r + 1) & 1][0] = NTL(hn); hv[(r + 1) & 1][1] = NTL(hn + 4); hv[(r + 1) & 1][2] = NTL(hn + 128); hv[(r + 1) & 1][3] = NTL(hn + 132);
;                 pv[(r + 1) & 1][0] = *(const u32x4*)pn; pv[(r + 1) & 1][1] = *(const u32x4*)(pn + 128); rs[(r + 1) & 1] = rss2[rn]; }
;             float* hp = H + (size_t)row * DM + col0; float ss = 0.f; const float rstd = rsqrtf(rs[r & 1] * (1.0f / DM) + 1e-6f);
; #pragma unroll
;             for (int bj = 0; bj < 2; ++bj) { const u32x4 pw = pv[r & 1][bj];
;                 const f32x4 b0 = *(const f32x4*)(bias + col0 + bj * 128), b1 = *(const f32x4*)(bias + col0 + bj * 128 + 4);
;                 const f32x4 p0 = (f32x4){bf_lo(pw.x), bf_hi(pw.x), bf_lo(pw.y), bf_hi(pw.y)}, p1 = (f32x4){bf_lo(pw.z), bf_hi(pw.z), bf_lo(pw.w), bf_hi(pw.w)};
;                 f32x4 g0 = acc[ai][bj][m][0] * rstd + b0, g1 = acc[ai][bj][m][1] * rstd + b1;
; #pragma unroll
;                 for (int j = 0; j < 4; ++j) { g0[j] = sigmoidf_(g0[j]); g1[j] = sigmoidf_(g1[j]); }
;                 const f32x4 v0 = hv[r & 1][2 * bj] + p0 * g0, v1 = hv[r & 1][2 * bj + 1] + p1 * g1;
;                 NTS(v0, hp + bj * 128); NTS(v1, hp + bj * 128 + 4);
; #pragma unroll
;                 for (int j = 0; j < 4; ++j) ss += v0[j] * v0[j] + v1[j] * v1[j]; }
;             ss += __shfl_xor(ss, 16); ss += __shfl_xor(ss, 32);
;             if (fq == 0) unsafeAtomicAdd(rss3 + row, ss); __builtin_amdgcn_sched_barrier(0); }
	v_add_f32_e32 v228, v228, v229
	v_add_f32_e32 v205, v205, v164
	v_add_f32_e32 v228, v228, v205
	s_mov_b64 s[66:67], exec
	s_and_b64 exec, exec, s[42:43]
	global_atomic_add_f32 v165, v202, v228, s[36:37] offset:512 sc0
	s_mov_b64 exec, s[66:67]
	v_pk_mul_f32 v[46:47], v[46:47], v[206:207]
	v_pk_mul_f32 v[48:49], v[48:49], v[206:207]
	v_pk_mul_f32 v[42:43], v[42:43], v[206:207]
	v_pk_mul_f32 v[44:45], v[44:45], v[206:207]
	v_exp_f32_e32 v46, v46
	v_exp_f32_e32 v47, v47
	v_exp_f32_e32 v48, v48
	v_exp_f32_e32 v49, v49
	v_exp_f32_e32 v42, v42
	v_exp_f32_e32 v43, v43
	v_exp_f32_e32 v44, v44
	v_exp_f32_e32 v45, v45
	v_pk_add_f32 v[46:47], v[46:47], 1.0 op_sel_hi:[1,0]
	v_pk_add_f32 v[48:49], v[48:49], 1.0 op_sel_hi:[1,0]
	v_pk_add_f32 v[42:43], v[42:43], 1.0 op_sel_hi:[1,0]
	v_pk_add_f32 v[44:45], v[44:45], 1.0 op_sel_hi:[1,0]
	v_rcp_f32_e32 v240, v46
	v_rcp_f32_e32 v241, v47
	v_rcp_f32_e32 v242, v48
	v_rcp_f32_e32 v243, v49
	v_rcp_f32_e32 v244, v42
	v_rcp_f32_e32 v245, v43
	v_rcp_f32_e32 v246, v44
	v_rcp_f32_e32 v247, v45
	v_pk_fma_f32 v[46:47], v[46:47], v[240:241], 1.0 op_sel_hi:[1,1,0] neg_lo:[1,0,0] neg_hi:[1,0,0]
	v_pk_fma_f32 v[48:49], v[48:49], v[242:243], 1.0 op_sel_hi:[1,1,0] neg_lo:[1,0,0] neg_hi:[1,0,0]
	v_pk_fma_f32 v[42:43], v[42:43], v[244:245], 1.0 op_sel_hi:[1,1,0] neg_lo:[1,0,0] neg_hi:[1,0,0]
	v_pk_fma_f32 v[44:45], v[44:45], v[246:247], 1.0 op_sel_hi:[1,1,0] neg_lo:[1,0,0] neg_hi:[1,0,0]
	v_pk_fma_f32 v[46:47], v[46:47], v[240:241], v[240:241]
	v_pk_fma_f32 v[48:49], v[48:49], v[242:243], v[242:243]
	v_pk_fma_f32 v[42:43], v[42:43], v[244:245], v[244:245]
	v_pk_fma_f32 v[44:45], v[44:45], v[246:247], v[246:247]
	v_pk_mul_f32 v[38:39], v[38:39], v[206:207]
	v_pk_mul_f32 v[40:41], v[40:41], v[206:207]
	v_pk_mul_f32 v[34:35], v[34:35], v[206:207]
	v_pk_mul_f32 v[36:37], v[36:37], v[206:207]
	v_exp_f32_e32 v38, v38
	v_exp_f32_e32 v39, v39
	v_exp_f32_e32 v40, v40
	v_exp_f32_e32 v41, v41
	v_exp_f32_e32 v34, v34
	v_exp_f32_e32 v35, v35
	v_exp_f32_e32 v36, v36
	v_exp_f32_e32 v37, v37
	v_pk_add_f32 v[38:39], v[38:39], 1.0 op_sel_hi:[1,0]
	v_pk_add_f32 v[40:41], v[40:41], 1.0 op_sel_hi:[1,0]
	v_pk_add_f32 v[34:35], v[34:35], 1.0 op_sel_hi:[1,0]
	v_pk_add_f32 v[36:37], v[36:37], 1.0 op_sel_hi:[1,0]
	v_rcp_f32_e32 v240, v38
	v_rcp_f32_e32 v241, v39
	v_rcp_f32_e32 v242, v40
	v_rcp_f32_e32 v243, v41
	v_rcp_f32_e32 v244, v34
	v_rcp_f32_e32 v245, v35
	v_rcp_f32_e32 v246, v36
	v_rcp_f32_e32 v247, v37
	v_pk_fma_f32 v[38:39], v[38:39], v[240:241], 1.0 op_sel_hi:[1,1,0] neg_lo:[1,0,0] neg_hi:[1,0,0]
	v_pk_fma_f32 v[40:41], v[40:41], v[242:243], 1.0 op_sel_hi:[1,1,0] neg_lo:[1,0,0] neg_hi:[1,0,0]
	v_pk_fma_f32 v[34:35], v[34:35], v[244:245], 1.0 op_sel_hi:[1,1,0] neg_lo:[1,0,0] neg_hi:[1,0,0]
	v_pk_fma_f32 v[36:37], v[36:37], v[246:247], 1.0 op_sel_hi:[1,1,0] neg_lo:[1,0,0] neg_hi:[1,0,0]
	v_pk_fma_f32 v[38:39], v[38:39], v[240:241], v[240:241]
	v_pk_fma_f32 v[40:41], v[40:41], v[242:243], v[242:243]
	v_pk_fma_f32 v[34:35], v[34:35], v[244:245], v[244:245]
	v_pk_fma_f32 v[36:37], v[36:37], v[246:247], v[246:247]
	s_waitcnt vmcnt(8)
	v_lshlrev_b32_e32 v248, 16, v154
	v_and_b32_e32 v249, 0xffff0000, v154
	v_lshlrev_b32_e32 v250, 16, v155
	v_and_b32_e32 v251, 0xffff0000, v155
	v_fma_f32 v46, v248, v46, v184
	v_fma_f32 v47, v249, v47, v185
	v_fma_f32 v48, v250, v48, v186
	v_fma_f32 v49, v251, v49, v187
	v_pk_mul_f32 v[228:229], v[46:47], v[46:47]
	s_nop 0
	v_pk_fma_f32 v[228:229], v[48:49], v[48:49], v[228:229]
	v_lshlrev_b32_e32 v232, 16, v156
	v_and_b32_e32 v233, 0xffff0000, v156
	v_lshlrev_b32_e32 v234, 16, v157
	v_and_b32_e32 v235, 0xffff0000, v157
	v_fma_f32 v42, v232, v42, v188
	v_fma_f32 v43, v233, v43, v189
	v_fma_f32 v44, v234, v44, v190
	v_fma_f32 v45, v235, v45, v191
	v_pk_fma_f32 v[228:229], v[42:43], v[42:43], v[228:229]
	s_nop 0
	v_pk_fma_f32 v[228:229], v[44:45], v[44:45], v[228:229]
	v_lshlrev_b32_e32 v248, 16, v158
	v_and_b32_e32 v249, 0xffff0000, v158
	v_lshlrev_b32_e32 v250, 16, v159
	v_and_b32_e32 v251, 0xffff0000, v159
	v_fma_f32 v38, v248, v38, v192
	v_fma_f32 v39, v249, v39, v193
	v_fma_f32 v40, v250, v40, v194
	v_fma_f32 v41, v251, v41, v195
	v_pk_fma_f32 v[228:229], v[38:39], v[38:39], v[228:229]
	s_nop 0
	v_pk_fma_f32 v[228:229], v[40:41], v[40:41], v[228:229]
	v_lshlrev_b32_e32 v232, 16, v160
	v_and_b32_e32 v233, 0xffff0000, v160
	v_lshlrev_b32_e32 v234, 16, v161
	v_and_b32_e32 v235, 0xffff0000, v161
	v_fma_f32 v34, v232, v34, v196
	v_fma_f32 v35, v233, v35, v197
	v_fma_f32 v36, v234, v36, v198
	v_fma_f32 v37, v235, v37, v199
	v_pk_fma_f32 v[228:229], v[34:35], v[34:35], v[228:229]
	s_nop 0
	v_pk_fma_f32 v[228:229], v[36:37], v[36:37], v[228:229]
	s_add_u32 s62, s22, 0xb0000
	s_addc_u32 s63, s23, 0
	global_load_dwordx4 v[184:187], v200, s[62:63] nt
	global_load_dwordx4 v[188:191], v200, s[62:63] offset:16 nt
	global_load_dwordx4 v[192:195], v200, s[62:63] offset:512 nt
	global_load_dwordx4 v[196:199], v200, s[62:63] offset:528 nt
	s_add_u32 s64, s2, 0x16000
	s_addc_u32 s65, s3, 0
	global_load_dwordx4 v[154:157], v201, s[64:65]
	global_load_dwordx4 v[158:161], v201, s[64:65] offset:256
	s_nop 0
	v_add_f32_e32 v228, v228, v229
	ds_bpermute_b32 v229, v225, v228
	ds_bpermute_b32 v205, v226, v228
	ds_bpermute_b32 v164, v227, v228
	s_waitcnt lgkmcnt(0)
; #define NTL(p) __builtin_nontemporal_load((const f32x4*)(p))
; #define NTS(v, p) __builtin_nontemporal_store((v), (f32x4*)(p))
; __device__ __forceinline__ float bf_lo(unsigned w) { return __uint_as_float(w << 16); }
; __device__ __forceinline__ float bf_hi(unsigned w) { return __uint_as_float(w & 0xffff0000u); }
; __device__ __forceinline__ float sigmoidf_(float x) { return 1.0f / (1.0f + __expf(-x)); }
;     __device__ __forceinline__ void operator()(AccT& acc, const Unit& u, int wr, int wc, int fr, int fq) const {
;     ...
;         for (int r = 0; r < 8; ++r) { const int ai = r >> 2, m = r & 3; const int row = row0 + ai * 128 + m * 16;
;             if (r < 7) { const int rn = row0 + ((r + 1) >> 2) * 128 + ((r + 1) & 3) * 16; const float* hn = H + (size_t)rn * DM + col0; const bf16_t* pn = ppbase + (((r + 1) >> 2) * 128 + ((r + 1) & 3) * 16) * 256;
;                 hv[(r + 1) & 1][0] = NTL(hn); hv[(r + 1) & 1][1] = NTL(hn + 4); hv[(r + 1) & 1][2] = NTL(hn + 128); hv[(r + 1) & 1][3] = NTL(hn + 132);
;                 pv[(r + 1) & 1][0] = *(const u32x4*)pn; pv[(r + 1) & 1][1] = *(const u32x4*)(pn + 128); rs[(r + 1) & 1] = rss2[rn]; }
;             float* hp = H + (size_t)row * DM + col0; float ss = 0.f; const float rstd = rsqrtf(rs[r & 1] * (1.0f / DM) + 1e-6f);
; #pragma unroll
;             for (int bj = 0; bj < 2; ++bj) { const u32x4 pw = pv[r & 1][bj];
;                 const f32x4 b0 = *(const f32x4*)(bias + col0 + bj * 128), b1 = *(const f32x4*)(bias + col0 + bj * 128 + 4);
;                 const f32x4 p0 = (f32x4){bf_lo(pw.x), bf_hi(pw.x), bf_lo(pw.y), bf_hi(pw.y)}, p1 = (f32x4){bf_lo(pw.z), bf_hi(pw.z), bf_lo(pw.w), bf_hi(pw.w)};
;                 f32x4 g0 = acc[ai][bj][m][0] * rstd + b0, g1 = acc[ai][bj][m][1] * rstd + b1;
; #pragma unroll
;                 for (int j = 0; j < 4; ++j) { g0[j] = sigmoidf_(g0[j]); g1[j] = sigmoidf_(g1[j]); }
;                 const f32x4 v0 = hv[r & 1][2 * bj] + p0 * g0, v1 = hv[r & 1][2 * bj + 1] + p1 * g1;
;                 NTS(v0, hp + bj * 128); NTS(v1, hp + bj * 128 + 4);
; #pragma unroll
;                 for (int j = 0; j < 4; ++j) ss += v0[j] * v0[j] + v1[j] * v1[j]; }
;             ss += __shfl_xor(ss, 16); ss += __shfl_xor(ss, 32);
;             if (fq == 0) unsafeAtomicAdd(rss3 + row, ss); __builtin_amdgcn_sched_barrier(0); }
	v_add_f32_e32 v228, v228, v229
	v_add_f32_e32 v205, v205, v164
	v_add_f32_e32 v228, v228, v205
	s_mov_b64 s[66:67], exec
	s_and_b64 exec, exec, s[42:43]
	global_atomic_add_f32 v165, v202, v228, s[36:37] offset:576 sc0
	s_mov_b64 exec, s[66:67]
	v_pk_mul_f32 v[30:31], v[30:31], v[206:207]
	v_pk_mul_f32 v[32:33], v[32:33], v[206:207]
	v_pk_mul_f32 v[26:27], v[26:27], v[206:207]
	v_pk_mul_f32 v[28:29], v[28:29], v[206:207]
	v_exp_f32_e32 v30, v30
	v_exp_f32_e32 v31, v31
	v_exp_f32_e32 v32, v32
	v_exp_f32_e32 v33, v33
	v_exp_f32_e32 v26, v26
	v_exp_f32_e32 v27, v27
	v_exp_f32_e32 v28, v28
	v_exp_f32_e32 v29, v29
	v_pk_add_f32 v[30:31], v[30:31], 1.0 op_sel_hi:[1,0]
	v_pk_add_f32 v[32:33], v[32:33], 1.0 op_sel_hi:[1,0]
	v_pk_add_f32 v[26:27], v[26:27], 1.0 op_sel_hi:[1,0]
	v_pk_add_f32 v[28:29], v[28:29], 1.0 op_sel_hi:[1,0]
	v_rcp_f32_e32 v240, v30
	v_rcp_f32_e32 v241, v31
	v_rcp_f32_e32 v242, v32
	v_rcp_f32_e32 v243, v33
	v_rcp_f32_e32 v244, v26
	v_rcp_f32_e32 v245, v27
	v_rcp_f32_e32 v246, v28
	v_rcp_f32_e32 v247, v29
	v_pk_fma_f32 v[30:31], v[30:31], v[240:241], 1.0 op_sel_hi:[1,1,0] neg_lo:[1,0,0] neg_hi:[1,0,0]
	v_pk_fma_f32 v[32:33], v[32:33], v[242:243], 1.0 op_sel_hi:[1,1,0] neg_lo:[1,0,0] neg_hi:[1,0,0]
	v_pk_fma_f32 v[26:27], v[26:27], v[244:245], 1.0 op_sel_hi:[1,1,0] neg_lo:[1,0,0] neg_hi:[1,0,0]
	v_pk_fma_f32 v[28:29], v[28:29], v[246:247], 1.0 op_sel_hi:[1,1,0] neg_lo:[1,0,0] neg_hi:[1,0,0]
	v_pk_fma_f32 v[30:31], v[30:31], v[240:241], v[240:241]
	v_pk_fma_f32 v[32:33], v[32:33], v[242:243], v[242:243]
	v_pk_fma_f32 v[26:27], v[26:27], v[244:245], v[244:245]
	v_pk_fma_f32 v[28:29], v[28:29], v[246:247], v[246:247]
	v_pk_mul_f32 v[22:23], v[22:23], v[206:207]
	v_pk_mul_f32 v[24:25], v[24:25], v[206:207]
	v_pk_mul_f32 v[18:19], v[18:19], v[206:207]
	v_pk_mul_f32 v[20:21], v[20:21], v[206:207]
	v_exp_f32_e32 v22, v22
	v_exp_f32_e32 v23, v23
	v_exp_f32_e32 v24, v24
	v_exp_f32_e32 v25, v25
	v_exp_f32_e32 v18, v18
	v_exp_f32_e32 v19, v19
	v_exp_f32_e32 v20, v20
	v_exp_f32_e32 v21, v21
	v_pk_add_f32 v[22:23], v[22:23], 1.0 op_sel_hi:[1,0]
	v_pk_add_f32 v[24:25], v[24:25], 1.0 op_sel_hi:[1,0]
	v_pk_add_f32 v[18:19], v[18:19], 1.0 op_sel_hi:[1,0]
	v_pk_add_f32 v[20:21], v[20:21], 1.0 op_sel_hi:[1,0]
	v_rcp_f32_e32 v240, v22
	v_rcp_f32_e32 v241, v23
	v_rcp_f32_e32 v242, v24
	v_rcp_f32_e32 v243, v25
	v_rcp_f32_e32 v244, v18
	v_rcp_f32_e32 v245, v19
	v_rcp_f32_e32 v246, v20
	v_rcp_f32_e32 v247, v21
	v_pk_fma_f32 v[22:23], v[22:23], v[240:241], 1.0 op_sel_hi:[1,1,0] neg_lo:[1,0,0] neg_hi:[1,0,0]
	v_pk_fma_f32 v[24:25], v[24:25], v[242:243], 1.0 op_sel_hi:[1,1,0] neg_lo:[1,0,0] neg_hi:[1,0,0]
	v_pk_fma_f32 v[18:19], v[18:19], v[244:245], 1.0 op_sel_hi:[1,1,0] neg_lo:[1,0,0] neg_hi:[1,0,0]
	v_pk_fma_f32 v[20:21], v[20:21], v[246:247], 1.0 op_sel_hi:[1,1,0] neg_lo:[1,0,0] neg_hi:[1,0,0]
	v_pk_fma_f32 v[22:23], v[22:23], v[240:241], v[240:241]
	v_pk_fma_f32 v[24:25], v[24:25], v[242:243], v[242:243]
	v_pk_fma_f32 v[18:19], v[18:19], v[244:245], v[244:245]
	v_pk_fma_f32 v[20:21], v[20:21], v[246:247], v[246:247]
	s_waitcnt vmcnt(8)
	v_lshlrev_b32_e32 v248, 16, v146
	v_and_b32_e32 v249, 0xffff0000, v146
	v_lshlrev_b32_e32 v250, 16, v147
	v_and_b32_e32 v251, 0xffff0000, v147
	v_fma_f32 v30, v248, v30, v130
	v_fma_f32 v31, v249, v31, v131
	v_fma_f32 v32, v250, v32, v132
	v_fma_f32 v33, v251, v33, v133
	v_pk_mul_f32 v[228:229], v[30:31], v[30:31]
	s_nop 0
	v_pk_fma_f32 v[228:229], v[32:33], v[32:33], v[228:229]
	v_lshlrev_b32_e32 v232, 16, v148
	v_and_b32_e32 v233, 0xffff0000, v148
	v_lshlrev_b32_e32 v234, 16, v149
	v_and_b32_e32 v235, 0xffff0000, v149
	v_fma_f32 v26, v232, v26, v134
	v_fma_f32 v27, v233, v27, v135
	v_fma_f32 v28, v234, v28, v136
	v_fma_f32 v29, v235, v29, v137
	v_pk_fma_f32 v[228:229], v[26:27], v[26:27], v[228:229]
	s_nop 0
	v_pk_fma_f32 v[228:229], v[28:29], v[28:29], v[228:229]
	v_lshlrev_b32_e32 v248, 16, v150
	v_and_b32_e32 v249, 0xffff0000, v150
	v_lshlrev_b32_e32 v250, 16, v151
	v_and_b32_e32 v251, 0xffff0000, v151
	v_fma_f32 v22, v248, v22, v138
	v_fma_f32 v23, v249, v23, v139
	v_fma_f32 v24, v250, v24, v140
	v_fma_f32 v25, v251, v25, v141
	v_pk_fma_f32 v[228:229], v[22:23], v[22:23], v[228:229]
	s_nop 0
	v_pk_fma_f32 v[228:229], v[24:25], v[24:25], v[228:229]
	v_lshlrev_b32_e32 v232, 16, v152
	v_and_b32_e32 v233, 0xffff0000, v152
	v_lshlrev_b32_e32 v234, 16, v153
	v_and_b32_e32 v235, 0xffff0000, v153
	v_fma_f32 v18, v232, v18, v142
	v_fma_f32 v19, v233, v19, v143
	v_fma_f32 v20, v234, v20, v144
	v_fma_f32 v21, v235, v21, v145
	v_pk_fma_f32 v[228:229], v[18:19], v[18:19], v[228:229]
	s_nop 0
	v_pk_fma_f32 v[228:229], v[20:21], v[20:21], v[228:229]
	s_nop 0
	v_add_f32_e32 v228, v228, v229
	ds_bpermute_b32 v229, v225, v228
	ds_bpermute_b32 v205, v226, v228
	ds_bpermute_b32 v164, v227, v228
	s_waitcnt lgkmcnt(0)
; #define NTL(p) __builtin_nontemporal_load((const f32x4*)(p))
; #define NTS(v, p) __builtin_nontemporal_store((v), (f32x4*)(p))
; __device__ __forceinline__ float bf_lo(unsigned w) { return __uint_as_float(w << 16); }
; __device__ __forceinline__ float bf_hi(unsigned w) { return __uint_as_float(w & 0xffff0000u); }
; __device__ __forceinline__ float sigmoidf_(float x) { return 1.0f / (1.0f + __expf(-x)); }
;     __device__ __forceinline__ void operator()(AccT& acc, const Unit& u, int wr, int wc, int fr, int fq) const {
;     ...
;         for (int r = 0; r < 8; ++r) { const int ai = r >> 2, m = r & 3; const int row = row0 + ai * 128 + m * 16;
;             if (r < 7) { const int rn = row0 + ((r + 1) >> 2) * 128 + ((r + 1) & 3) * 16; const float* hn = H + (size_t)rn * DM + col0; const bf16_t* pn = ppbase + (((r + 1) >> 2) * 128 + ((r + 1) & 3) * 16) * 256;
;                 hv[(r + 1) & 1][0] = NTL(hn); hv[(r + 1) & 1][1] = NTL(hn + 4); hv[(r + 1) & 1][2] = NTL(hn + 128); hv[(r + 1) & 1][3] = NTL(hn + 132);
;                 pv[(r + 1) & 1][0] = *(const u32x4*)pn; pv[(r + 1) & 1][1] = *(const u32x4*)(pn + 128); rs[(r + 1) & 1] = rss2[rn]; }
;             float* hp = H + (size_t)row * DM + col0; float ss = 0.f; const float rstd = rsqrtf(rs[r & 1] * (1.0f / DM) + 1e-6f);
; #pragma unroll
;             for (int bj = 0; bj < 2; ++bj) { const u32x4 pw = pv[r & 1][bj];
;                 const f32x4 b0 = *(const f32x4*)(bias + col0 + bj * 128), b1 = *(const f32x4*)(bias + col0 + bj * 128 + 4);
;                 const f32x4 p0 = (f32x4){bf_lo(pw.x), bf_hi(pw.x), bf_lo(pw.y), bf_hi(pw.y)}, p1 = (f32x4){bf_lo(pw.z), bf_hi(pw.z), bf_lo(pw.w), bf_hi(pw.w)};
;                 f32x4 g0 = acc[ai][bj][m][0] * rstd + b0, g1 = acc[ai][bj][m][1] * rstd + b1;
; #pragma unroll
;                 for (int j = 0; j < 4; ++j) { g0[j] = sigmoidf_(g0[j]); g1[j] = sigmoidf_(g1[j]); }
;                 const f32x4 v0 = hv[r & 1][2 * bj] + p0 * g0, v1 = hv[r & 1][2 * bj + 1] + p1 * g1;
;                 NTS(v0, hp + bj * 128); NTS(v1, hp + bj * 128 + 4);
; #pragma unroll
;                 for (int j = 0; j < 4; ++j) ss += v0[j] * v0[j] + v1[j] * v1[j]; }
;             ss += __shfl_xor(ss, 16); ss += __shfl_xor(ss, 32);
;             if (fq == 0) unsafeAtomicAdd(rss3 + row, ss); __builtin_amdgcn_sched_barrier(0); }
	v_add_f32_e32 v228, v228, v229
	v_add_f32_e32 v205, v205, v164
	v_add_f32_e32 v228, v228, v205
	s_mov_b64 s[66:67], exec
	s_and_b64 exec, exec, s[42:43]
	global_atomic_add_f32 v165, v202, v228, s[36:37] offset:640 sc0
	s_mov_b64 exec, s[66:67]
	v_pk_mul_f32 v[14:15], v[14:15], v[206:207]
	v_pk_mul_f32 v[16:17], v[16:17], v[206:207]
	v_pk_mul_f32 v[10:11], v[10:11], v[206:207]
	v_pk_mul_f32 v[12:13], v[12:13], v[206:207]
	v_exp_f32_e32 v14, v14
	v_exp_f32_e32 v15, v15
	v_exp_f32_e32 v16, v16
	v_exp_f32_e32 v17, v17
	v_exp_f32_e32 v10, v10
	v_exp_f32_e32 v11, v11
	v_exp_f32_e32 v12, v12
	v_exp_f32_e32 v13, v13
	v_pk_add_f32 v[14:15], v[14:15], 1.0 op_sel_hi:[1,0]
	v_pk_add_f32 v[16:17], v[16:17], 1.0 op_sel_hi:[1,0]
	v_pk_add_f32 v[10:11], v[10:11], 1.0 op_sel_hi:[1,0]
	v_pk_add_f32 v[12:13], v[12:13], 1.0 op_sel_hi:[1,0]
	v_rcp_f32_e32 v240, v14
	v_rcp_f32_e32 v241, v15
	v_rcp_f32_e32 v242, v16
	v_rcp_f32_e32 v243, v17
	v_rcp_f32_e32 v244, v10
	v_rcp_f32_e32 v245, v11
	v_rcp_f32_e32 v246, v12
	v_rcp_f32_e32 v247, v13
	v_pk_fma_f32 v[14:15], v[14:15], v[240:241], 1.0 op_sel_hi:[1,1,0] neg_lo:[1,0,0] neg_hi:[1,0,0]
	v_pk_fma_f32 v[16:17], v[16:17], v[242:243], 1.0 op_sel_hi:[1,1,0] neg_lo:[1,0,0] neg_hi:[1,0,0]
	v_pk_fma_f32 v[10:11], v[10:11], v[244:245], 1.0 op_sel_hi:[1,1,0] neg_lo:[1,0,0] neg_hi:[1,0,0]
	v_pk_fma_f32 v[12:13], v[12:13], v[246:247], 1.0 op_sel_hi:[1,1,0] neg_lo:[1,0,0] neg_hi:[1,0,0]
	v_pk_fma_f32 v[14:15], v[14:15], v[240:241], v[240:241]
	v_pk_fma_f32 v[16:17], v[16:17], v[242:243], v[242:243]
	v_pk_fma_f32 v[10:11], v[10:11], v[244:245], v[244:245]
	v_pk_fma_f32 v[12:13], v[12:13], v[246:247], v[246:247]
	v_pk_mul_f32 v[6:7], v[6:7], v[206:207]
	v_pk_mul_f32 v[8:9], v[8:9], v[206:207]
	v_pk_mul_f32 v[2:3], v[2:3], v[206:207]
	v_pk_mul_f32 v[4:5], v[4:5], v[206:207]
	v_exp_f32_e32 v6, v6
	v_exp_f32_e32 v7, v7
	v_exp_f32_e32 v8, v8
	v_exp_f32_e32 v9, v9
	v_exp_f32_e32 v2, v2
	v_exp_f32_e32 v3, v3
	v_exp_f32_e32 v4, v4
	v_exp_f32_e32 v5, v5
	v_pk_add_f32 v[6:7], v[6:7], 1.0 op_sel_hi:[1,0]
	v_pk_add_f32 v[8:9], v[8:9], 1.0 op_sel_hi:[1,0]
	v_pk_add_f32 v[2:3], v[2:3], 1.0 op_sel_hi:[1,0]
	v_pk_add_f32 v[4:5], v[4:5], 1.0 op_sel_hi:[1,0]
	v_rcp_f32_e32 v240, v6
	v_rcp_f32_e32 v241, v7
	v_rcp_f32_e32 v242, v8
	v_rcp_f32_e32 v243, v9
	v_rcp_f32_e32 v244, v2
	v_rcp_f32_e32 v245, v3
	v_rcp_f32_e32 v246, v4
	v_rcp_f32_e32 v247, v5
	v_pk_fma_f32 v[6:7], v[6:7], v[240:241], 1.0 op_sel_hi:[1,1,0] neg_lo:[1,0,0] neg_hi:[1,0,0]
	v_pk_fma_f32 v[8:9], v[8:9], v[242:243], 1.0 op_sel_hi:[1,1,0] neg_lo:[1,0,0] neg_hi:[1,0,0]
	v_pk_fma_f32 v[2:3], v[2:3], v[244:245], 1.0 op_sel_hi:[1,1,0] neg_lo:[1,0,0] neg_hi:[1,0,0]
	v_pk_fma_f32 v[4:5], v[4:5], v[246:247], 1.0 op_sel_hi:[1,1,0] neg_lo:[1,0,0] neg_hi:[1,0,0]
	v_pk_fma_f32 v[6:7], v[6:7], v[240:241], v[240:241]
	v_pk_fma_f32 v[8:9], v[8:9], v[242:243], v[242:243]
	v_pk_fma_f32 v[2:3], v[2:3], v[244:245], v[244:245]
	v_pk_fma_f32 v[4:5], v[4:5], v[246:247], v[246:247]
	s_waitcnt vmcnt(2)
	v_lshlrev_b32_e32 v248, 16, v154
	v_and_b32_e32 v249, 0xffff0000, v154
	v_lshlrev_b32_e32 v250, 16, v155
	v_and_b32_e32 v251, 0xffff0000, v155
	v_fma_f32 v14, v248, v14, v184
	v_fma_f32 v15, v249, v15, v185
	v_fma_f32 v16, v250, v16, v186
	v_fma_f32 v17, v251, v17, v187
	v_pk_mul_f32 v[228:229], v[14:15], v[14:15]
	s_nop 0
	v_pk_fma_f32 v[228:229], v[16:17], v[16:17], v[228:229]
	v_lshlrev_b32_e32 v232, 16, v156
	v_and_b32_e32 v233, 0xffff0000, v156
	v_lshlrev_b32_e32 v234, 16, v157
	v_and_b32_e32 v235, 0xffff0000, v157
	v_fma_f32 v10, v232, v10, v188
	v_fma_f32 v11, v233, v11, v189
	v_fma_f32 v12, v234, v12, v190
	v_fma_f32 v13, v235, v13, v191
	v_pk_fma_f32 v[228:229], v[10:11], v[10:11], v[228:229]
	s_nop 0
	v_pk_fma_f32 v[228:229], v[12:13], v[12:13], v[228:229]
	v_lshlrev_b32_e32 v248, 16, v158
	v_and_b32_e32 v249, 0xffff0000, v158
	v_lshlrev_b32_e32 v250, 16, v159
	v_and_b32_e32 v251, 0xffff0000, v159
	v_fma_f32 v6, v248, v6, v192
	v_fma_f32 v7, v249, v7, v193
	v_fma_f32 v8, v250, v8, v194
	v_fma_f32 v9, v251, v9, v195
	v_pk_fma_f32 v[228:229], v[6:7], v[6:7], v[228:229]
	s_nop 0
	v_pk_fma_f32 v[228:229], v[8:9], v[8:9], v[228:229]
	v_lshlrev_b32_e32 v232, 16, v160
	v_and_b32_e32 v233, 0xffff0000, v160
	v_lshlrev_b32_e32 v234, 16, v161
	v_and_b32_e32 v235, 0xffff0000, v161
	v_fma_f32 v2, v232, v2, v196
	v_fma_f32 v3, v233, v3, v197
	v_fma_f32 v4, v234, v4, v198
	v_fma_f32 v5, v235, v5, v199
	v_pk_fma_f32 v[228:229], v[2:3], v[2:3], v[228:229]
	s_nop 0
	v_pk_fma_f32 v[228:229], v[4:5], v[4:5], v[228:229]
	s_nop 0
	v_add_f32_e32 v228, v228, v229
	ds_bpermute_b32 v229, v225, v228
	ds_bpermute_b32 v205, v226, v228
	ds_bpermute_b32 v164, v227, v228
	s_waitcnt lgkmcnt(0)
	v_add_f32_e32 v228, v228, v229
	v_add_f32_e32 v205, v205, v164
	v_add_f32_e32 v228, v228, v205
	s_mov_b64 s[66:67], exec
	s_and_b64 exec, exec, s[42:43]
	global_atomic_add_f32 v165, v202, v228, s[36:37] offset:704 sc0
	s_mov_b64 exec, s[66:67]
	s_waitcnt vmcnt(0)
	s_barrier
	s_barrier
	s_lshr_b32 s60, s60, 8
	s_lshl_b32 s60, s60, 2
	s_add_u32 s62, s36, 0x20000
	s_addc_u32 s63, s37, 0
	s_add_u32 s62, s62, s60
	s_addc_u32 s63, s63, 0
	v_cmp_eq_u32_e32 vcc, 0, v162
	s_and_saveexec_b64 s[66:67], vcc
	s_cbranch_execz .Lpg_met
	v_mov_b32_e32 v205, 0
	v_mov_b32_e32 v228, 1
	global_atomic_add v229, v205, v228, s[62:63] sc0
	s_waitcnt vmcnt(0)
	s_mov_b32 s61, 0
